# v42 plus streaming (nt) hint on the gate_up phase result stores so activation row blocks stay in L2
# baseline (speedup 1.0000x reference)
; __device__ __forceinline__ float row_part(const float* ss, int row, int fq) { const f32x4 a = ((const f32x4*)(ss + (size_t)row * 16))[fq]; return (a[0] + a[1]) + (a[2] + a[3]); }
; __device__ __forceinline__ float row_finish(float t) { t += shx(t, 16); t += shx(t, 32); return __builtin_amdgcn_rsqf(t * (1.0f / 1024.0f) + RMS_EPS); }
;     __device__ __forceinline__ void operator()(const f32x4 (&acc)[2][2][4][2], const Unit& u, int wr, int wc, int fr, int fq) const {
;         const int col0 = u.pn * 128 + 32 * wc + 8 * fq;
;         float rs[2][4];
; #pragma unroll
;         for (int ai = 0; ai < 2; ++ai)
; #pragma unroll
;             for (int m = 0; m < 4; ++m) rs[ai][m] = row_part(ss, u.pm * BM + ai * HALF + wr * 64 + m * 16 + fr, fq);
; #pragma unroll
;         for (int ai = 0; ai < 2; ++ai)
; #pragma unroll
;             for (int m = 0; m < 4; ++m) rs[ai][m] = row_finish(rs[ai][m]);
.LBB0_523:
	v_lshl_add_u32 v170, s36, 8, v153
	v_ashrrev_i32_e32 v171, 31, v170
	v_or_b32_e32 v166, 16, v170
	v_lshlrev_b64 v[146:147], 6, v[170:171]
	v_ashrrev_i32_e32 v167, 31, v166
	v_lshl_add_u64 v[146:147], v[136:137], 0, v[146:147]
	v_lshlrev_b64 v[148:149], 6, v[166:167]
	v_lshl_add_u64 v[148:149], v[136:137], 0, v[148:149]
	ds_read_b128 v[176:179], v239
	ds_read_b128 v[180:183], v239 offset:1024
	v_or_b32_e32 v162, 32, v170
	v_ashrrev_i32_e32 v163, 31, v162
	v_or_b32_e32 v158, 48, v170
	v_lshlrev_b64 v[146:147], 6, v[162:163]
	v_ashrrev_i32_e32 v159, 31, v158
	v_lshl_add_u64 v[146:147], v[136:137], 0, v[146:147]
	v_lshlrev_b64 v[148:149], 6, v[158:159]
	v_lshl_add_u64 v[148:149], v[136:137], 0, v[148:149]
	ds_read_b128 v[184:187], v239 offset:2048
	ds_read_b128 v[188:191], v239 offset:3072
	v_add_u32_e32 v154, 0x80, v170
	v_ashrrev_i32_e32 v155, 31, v154
	v_add_u32_e32 v150, 0x90, v170
	v_lshlrev_b64 v[146:147], 6, v[154:155]
	v_ashrrev_i32_e32 v151, 31, v150
	v_lshl_add_u64 v[146:147], v[136:137], 0, v[146:147]
	v_lshlrev_b64 v[148:149], 6, v[150:151]
	v_lshl_add_u64 v[148:149], v[136:137], 0, v[148:149]
	ds_read_b128 v[192:195], v239 offset:8192
	ds_read_b128 v[196:199], v239 offset:9216
	v_add_u32_e32 v148, 0xa0, v170
	v_ashrrev_i32_e32 v149, 31, v148
	v_lshlrev_b64 v[146:147], 6, v[148:149]
	v_lshl_add_u64 v[146:147], v[136:137], 0, v[146:147]
	ds_read_b128 v[202:205], v239 offset:10240
	v_add_u32_e32 v146, 0xb0, v170
	v_ashrrev_i32_e32 v147, 31, v146
	v_lshlrev_b64 v[206:207], 6, v[146:147]
	v_lshl_add_u64 v[206:207], v[136:137], 0, v[206:207]
	ds_read_b128 v[206:209], v239 offset:11264
	v_mov_b32_e32 v147, v201
	v_mov_b32_e32 v149, v201
	v_lshlrev_b32_e32 v147, 2, v147
	v_mov_b32_e32 v151, v201
	v_xor_b32_e32 v147, 64, v147
	s_andn2_b64 vcc, exec, s[10:11]
	v_lshlrev_b32_e32 v151, 2, v151
	v_xor_b32_e32 v151, 64, v151
	v_lshlrev_b32_e32 v149, 2, v149
	v_xor_b32_e32 v149, 0x80, v149
	s_mov_b64 s[10:11], -1
	s_waitcnt lgkmcnt(0)
	v_mov_b32_e32 v210, v177
	v_mov_b32_e32 v211, v178
	v_mov_b32_e32 v177, v179
	v_pk_add_f32 v[176:177], v[210:211], v[176:177]
	v_mov_b32_e32 v178, v181
	v_add_f32_e32 v152, v176, v177
	v_mov_b32_e32 v179, v182
	v_mov_b32_e32 v181, v183
	v_mov_b32_e32 v147, v152
	s_nop 1
	v_permlane16_swap_b32_e32 v147, v152
	v_pk_add_f32 v[176:177], v[178:179], v[180:181]
	v_mov_b32_e32 v182, v185
	v_add_f32_e32 v155, v176, v177
	v_mov_b32_e32 v151, v155
	s_nop 1
	v_permlane16_swap_b32_e32 v151, v155
	s_waitcnt lgkmcnt(0)
	v_add_f32_e32 v147, v152, v147
	v_mov_b32_e32 v152, v201
	v_mov_b32_e32 v149, v147
	s_nop 1
	v_permlane32_swap_b32_e32 v149, v147
	s_waitcnt lgkmcnt(0)
	v_add_f32_e32 v151, v155, v151
	v_lshlrev_b32_e32 v152, 2, v152
	v_xor_b32_e32 v152, 0x80, v152
	v_mov_b32_e32 v152, v151
	s_nop 1
	v_permlane32_swap_b32_e32 v152, v151
	s_waitcnt lgkmcnt(0)
	v_add_f32_e32 v147, v147, v149
	v_mov_b32_e32 v149, v201
	v_mov_b32_e32 v183, v186
	v_mov_b32_e32 v185, v187
	v_pk_add_f32 v[178:179], v[182:183], v[184:185]
	v_fmamk_f32 v147, v147, 0x3a800000, v175
	v_lshlrev_b32_e32 v149, 2, v149
	v_add_f32_e32 v156, v178, v179
	v_rsq_f32_e32 v176, v147
	s_waitcnt lgkmcnt(0)
	v_add_f32_e32 v147, v151, v152
	v_xor_b32_e32 v149, 64, v149
	v_mov_b32_e32 v151, v201
	v_mov_b32_e32 v152, v201
	v_mov_b32_e32 v186, v189
	v_mov_b32_e32 v187, v190
	v_mov_b32_e32 v189, v191
	v_mov_b32_e32 v149, v156
	s_nop 1
	v_permlane16_swap_b32_e32 v149, v156
	v_pk_add_f32 v[180:181], v[186:187], v[188:189]
	v_lshlrev_b32_e32 v152, 2, v152
	v_add_f32_e32 v159, v180, v181
	v_xor_b32_e32 v152, 64, v152
	v_mov_b32_e32 v152, v159
	s_nop 1
	v_permlane16_swap_b32_e32 v152, v159
	s_waitcnt lgkmcnt(0)
	v_add_f32_e32 v149, v156, v149
	v_lshlrev_b32_e32 v151, 2, v151
	v_mov_b32_e32 v156, v201
	v_xor_b32_e32 v151, 0x80, v151
	v_mov_b32_e32 v151, v149
	s_nop 1
	v_permlane32_swap_b32_e32 v151, v149
	v_lshlrev_b32_e32 v156, 2, v156
	s_waitcnt lgkmcnt(0)
	v_add_f32_e32 v152, v159, v152
	v_xor_b32_e32 v156, 0x80, v156
	v_mov_b32_e32 v156, v152
	s_nop 1
	v_permlane32_swap_b32_e32 v156, v152
	v_fmamk_f32 v147, v147, 0x3a800000, v175
	v_rsq_f32_e32 v174, v147
	s_waitcnt lgkmcnt(0)
	v_add_f32_e32 v147, v149, v151
	v_mov_b32_e32 v149, v201
	v_mov_b32_e32 v190, v193
	v_mov_b32_e32 v191, v194
	v_mov_b32_e32 v193, v195
	v_fmamk_f32 v147, v147, 0x3a800000, v175
	v_pk_add_f32 v[182:183], v[190:191], v[192:193]
	v_rsq_f32_e32 v172, v147
	s_waitcnt lgkmcnt(0)
	v_add_f32_e32 v147, v152, v156
	v_lshlrev_b32_e32 v149, 2, v149
	v_mov_b32_e32 v151, v201
	v_mov_b32_e32 v152, v201
	v_mov_b32_e32 v194, v197
	v_mov_b32_e32 v195, v198
	v_mov_b32_e32 v197, v199
	v_add_f32_e32 v160, v182, v183
	v_xor_b32_e32 v149, 64, v149
	v_pk_add_f32 v[184:185], v[194:195], v[196:197]
	v_mov_b32_e32 v149, v160
	s_nop 1
	v_permlane16_swap_b32_e32 v149, v160
	v_lshlrev_b32_e32 v152, 2, v152
	v_add_f32_e32 v163, v184, v185
	v_xor_b32_e32 v152, 64, v152
	v_mov_b32_e32 v152, v163
	s_nop 1
	v_permlane16_swap_b32_e32 v152, v163
	v_lshlrev_b32_e32 v151, 2, v151
	v_mov_b32_e32 v156, v201
	s_waitcnt lgkmcnt(0)
	v_add_f32_e32 v149, v160, v149
	v_xor_b32_e32 v151, 0x80, v151
	v_mov_b32_e32 v151, v149
	s_nop 1
	v_permlane32_swap_b32_e32 v151, v149
	v_lshlrev_b32_e32 v156, 2, v156
	s_waitcnt lgkmcnt(0)
	v_add_f32_e32 v152, v163, v152
	v_xor_b32_e32 v156, 0x80, v156
	v_mov_b32_e32 v156, v152
	s_nop 1
	v_permlane32_swap_b32_e32 v156, v152
	v_fmamk_f32 v147, v147, 0x3a800000, v175
	v_rsq_f32_e32 v168, v147
	s_waitcnt lgkmcnt(0)
	v_add_f32_e32 v147, v149, v151
	v_fmamk_f32 v147, v147, 0x3a800000, v175
	v_rsq_f32_e32 v164, v147
	s_waitcnt lgkmcnt(0)
; __device__ __forceinline__ float row_finish(float t) { t += shx(t, 16); t += shx(t, 32); return __builtin_amdgcn_rsqf(t * (1.0f / 1024.0f) + RMS_EPS); }
; __device__ __forceinline__ f32x4 silu4(f32x4 v) { return (f32x4){silu_f(v[0]), silu_f(v[1]), silu_f(v[2]), silu_f(v[3])}; }
; __device__ __forceinline__ u32x4 pack8(f32x4 a, f32x4 b) { u32x4 w; w.x = cvt_pk_bf16(a[0], a[1]); w.y = cvt_pk_bf16(a[2], a[3]); w.z = cvt_pk_bf16(b[0], b[1]); w.w = cvt_pk_bf16(b[2], b[3]); return w; }
;     __device__ __forceinline__ void operator()(const f32x4 (&acc)[2][2][4][2], const Unit& u, int wr, int wc, int fr, int fq) const {
;     ...
;             for (int m = 0; m < 4; ++m) rs[ai][m] = row_finish(rs[ai][m]);
; #pragma unroll
;         for (int ai = 0; ai < 2; ++ai)
; #pragma unroll
;             for (int m = 0; m < 4; ++m) {
;                 const int row = u.pm * BM + ai * HALF + wr * 64 + m * 16 + fr;
;                 const float rstd = rs[ai][m];
;                 const f32x4 a0 = silu4(acc[ai][0][m][0] * rstd) * (acc[ai][1][m][0] * rstd);
;                 const f32x4 a1 = silu4(acc[ai][0][m][1] * rstd) * (acc[ai][1][m][1] * rstd);
;                 *(u32x4*)(ACT + (size_t)row * 2816 + col0) = pack8(a0, a1);
	v_add_f32_e32 v147, v152, v156
	v_mov_b32_e32 v149, v201
	v_mov_b32_e32 v151, v201
	v_mov_b32_e32 v152, v201
	v_mov_b32_e32 v198, v203
	v_mov_b32_e32 v199, v204
	v_mov_b32_e32 v203, v205
	v_mov_b32_e32 v204, v207
	v_mov_b32_e32 v205, v208
	v_mov_b32_e32 v207, v209
	v_pk_add_f32 v[188:189], v[204:205], v[206:207]
	v_lshlrev_b32_e32 v152, 2, v152
	v_pk_add_f32 v[186:187], v[198:199], v[202:203]
	v_add_f32_e32 v155, v188, v189
	v_lshlrev_b32_e32 v149, 2, v149
	v_xor_b32_e32 v152, 64, v152
	v_add_f32_e32 v167, v186, v187
	v_xor_b32_e32 v149, 64, v149
	v_mov_b32_e32 v152, v155
	s_nop 1
	v_permlane16_swap_b32_e32 v152, v155
	v_mov_b32_e32 v149, v167
	s_nop 1
	v_permlane16_swap_b32_e32 v149, v167
	v_lshlrev_b32_e32 v151, 2, v151
	v_xor_b32_e32 v151, 0x80, v151
	v_fmamk_f32 v147, v147, 0x3a800000, v175
	s_waitcnt lgkmcnt(0)
	v_add_f32_e32 v152, v155, v152
	v_mov_b32_e32 v155, v201
	s_waitcnt lgkmcnt(0)
	v_add_f32_e32 v149, v167, v149
	v_mov_b32_e32 v151, v149
	s_nop 1
	v_permlane32_swap_b32_e32 v151, v149
	v_lshlrev_b32_e32 v155, 2, v155
	v_xor_b32_e32 v155, 0x80, v155
	v_mov_b32_e32 v155, v152
	s_nop 1
	v_permlane32_swap_b32_e32 v155, v152
	v_rsq_f32_e32 v160, v147
	s_waitcnt lgkmcnt(0)
	v_add_f32_e32 v147, v149, v151
	v_fmamk_f32 v147, v147, 0x3a800000, v175
	v_rsq_f32_e32 v156, v147
	s_waitcnt lgkmcnt(0)
	v_add_f32_e32 v147, v152, v155
	v_fmamk_f32 v147, v147, 0x3a800000, v175
	v_pk_mul_f32 v[124:125], v[124:125], v[176:177] op_sel_hi:[1,0]
	v_rsq_f32_e32 v152, v147
	v_mul_f32_e32 v147, 0xbfb8aa3b, v124
	v_exp_f32_e32 v147, v147
	v_mul_f32_e32 v149, 0xbfb8aa3b, v125
	v_exp_f32_e32 v149, v149
	v_pk_mul_f32 v[126:127], v[126:127], v[176:177] op_sel_hi:[1,0]
	v_add_f32_e32 v147, 1.0, v147
	v_rcp_f32_e32 v178, v147
	v_add_f32_e32 v147, 1.0, v149
	v_mul_f32_e32 v149, 0xbfb8aa3b, v126
	v_exp_f32_e32 v149, v149
	v_mul_f32_e32 v151, 0xbfb8aa3b, v127
	v_exp_f32_e32 v151, v151
	v_rcp_f32_e32 v179, v147
	v_add_f32_e32 v147, 1.0, v149
	v_rcp_f32_e32 v180, v147
	v_add_f32_e32 v147, 1.0, v151
	v_pk_mul_f32 v[120:121], v[120:121], v[176:177] op_sel_hi:[1,0]
	v_rcp_f32_e32 v181, v147
	v_mul_f32_e32 v147, 0xbfb8aa3b, v120
	v_exp_f32_e32 v147, v147
	v_mul_f32_e32 v149, 0xbfb8aa3b, v121
	v_exp_f32_e32 v149, v149
	v_pk_mul_f32 v[122:123], v[122:123], v[176:177] op_sel_hi:[1,0]
	v_add_f32_e32 v147, 1.0, v147
	v_pk_mul_f32 v[124:125], v[124:125], v[178:179]
	v_rcp_f32_e32 v178, v147
	v_add_f32_e32 v147, 1.0, v149
	v_mul_f32_e32 v149, 0xbfb8aa3b, v122
	v_exp_f32_e32 v149, v149
	v_mul_f32_e32 v151, 0xbfb8aa3b, v123
	v_exp_f32_e32 v151, v151
	v_rcp_f32_e32 v179, v147
	v_add_f32_e32 v147, 1.0, v149
	v_pk_mul_f32 v[126:127], v[126:127], v[180:181]
	v_rcp_f32_e32 v180, v147
	v_add_f32_e32 v147, 1.0, v151
	v_rcp_f32_e32 v181, v147
	v_pk_mul_f32 v[116:117], v[116:117], v[176:177] op_sel_hi:[1,0]
	v_pk_mul_f32 v[118:119], v[118:119], v[176:177] op_sel_hi:[1,0]
	v_pk_mul_f32 v[120:121], v[120:121], v[178:179]
	v_pk_mul_f32 v[112:113], v[112:113], v[176:177] op_sel_hi:[1,0]
	v_lshl_or_b32 v182, s57, 7, v161
	v_pk_mul_f32 v[118:119], v[118:119], v[126:127]
	v_pk_mul_f32 v[116:117], v[116:117], v[124:125]
	v_pk_mul_f32 v[122:123], v[122:123], v[180:181]
	v_pk_mul_f32 v[114:115], v[114:115], v[176:177] op_sel_hi:[1,0]
	v_pk_mul_f32 v[112:113], v[112:113], v[120:121]
	v_ashrrev_i32_e32 v183, 31, v182
	v_pk_mul_f32 v[114:115], v[114:115], v[122:123]
	v_cvt_pk_bf16_f32 v116, v116, v117
	v_cvt_pk_bf16_f32 v117, v118, v119
	v_cvt_pk_bf16_f32 v118, v112, v113
	v_mov_b64_e32 v[112:113], s[14:15]
	v_cvt_pk_bf16_f32 v119, v114, v115
	v_mad_i64_i32 v[120:121], s[38:39], v170, s56, v[112:113]
	v_lshlrev_b64 v[114:115], 1, v[182:183]
	v_pk_mul_f32 v[108:109], v[108:109], v[174:175] op_sel_hi:[1,0]
	v_pk_mul_f32 v[110:111], v[110:111], v[174:175] op_sel_hi:[1,0]
	v_mul_f32_e32 v122, 0xbfb8aa3b, v108
	v_mul_f32_e32 v123, 0xbfb8aa3b, v109
	v_lshl_add_u64 v[120:121], v[120:121], 0, v[114:115]
	v_pk_mul_f32 v[104:105], v[104:105], v[174:175] op_sel_hi:[1,0]
	v_pk_mul_f32 v[106:107], v[106:107], v[174:175] op_sel_hi:[1,0]
	v_exp_f32_e32 v122, v122
	v_exp_f32_e32 v123, v123
	v_mul_f32_e32 v124, 0xbfb8aa3b, v110
	v_mul_f32_e32 v125, 0xbfb8aa3b, v111
	global_store_dwordx4 v[120:121], v[116:119], off nt
	v_exp_f32_e32 v124, v124
	v_exp_f32_e32 v125, v125
	v_mul_f32_e32 v116, 0xbfb8aa3b, v104
	v_mul_f32_e32 v117, 0xbfb8aa3b, v105
	v_mul_f32_e32 v118, 0xbfb8aa3b, v106
	v_mul_f32_e32 v119, 0xbfb8aa3b, v107
	v_exp_f32_e32 v116, v116
	v_exp_f32_e32 v117, v117
	v_exp_f32_e32 v118, v118
	v_exp_f32_e32 v119, v119
	v_add_f32_e32 v122, 1.0, v122
	v_add_f32_e32 v123, 1.0, v123
	v_rcp_f32_e32 v122, v122
	v_rcp_f32_e32 v123, v123
	v_add_f32_e32 v124, 1.0, v124
	v_add_f32_e32 v125, 1.0, v125
	v_add_f32_e32 v116, 1.0, v116
	v_add_f32_e32 v117, 1.0, v117
	v_add_f32_e32 v118, 1.0, v118
	v_add_f32_e32 v119, 1.0, v119
	v_rcp_f32_e32 v124, v124
	v_rcp_f32_e32 v125, v125
	v_rcp_f32_e32 v116, v116
	v_rcp_f32_e32 v117, v117
	v_rcp_f32_e32 v118, v118
	v_rcp_f32_e32 v119, v119
	v_pk_mul_f32 v[108:109], v[108:109], v[122:123]
	v_pk_mul_f32 v[100:101], v[100:101], v[174:175] op_sel_hi:[1,0]
	v_pk_mul_f32 v[110:111], v[110:111], v[124:125]
	v_pk_mul_f32 v[102:103], v[102:103], v[174:175] op_sel_hi:[1,0]
	v_pk_mul_f32 v[100:101], v[100:101], v[108:109]
	v_pk_mul_f32 v[104:105], v[104:105], v[116:117]
	v_pk_mul_f32 v[106:107], v[106:107], v[118:119]
	v_pk_mul_f32 v[96:97], v[96:97], v[174:175] op_sel_hi:[1,0]
	v_pk_mul_f32 v[98:99], v[98:99], v[174:175] op_sel_hi:[1,0]
	v_pk_mul_f32 v[102:103], v[102:103], v[110:111]
	v_pk_mul_f32 v[106:107], v[98:99], v[106:107]
	v_pk_mul_f32 v[98:99], v[96:97], v[104:105]
; __device__ __forceinline__ f32x4 silu4(f32x4 v) { return (f32x4){silu_f(v[0]), silu_f(v[1]), silu_f(v[2]), silu_f(v[3])}; }
; __device__ __forceinline__ u32x4 pack8(f32x4 a, f32x4 b) { u32x4 w; w.x = cvt_pk_bf16(a[0], a[1]); w.y = cvt_pk_bf16(a[2], a[3]); w.z = cvt_pk_bf16(b[0], b[1]); w.w = cvt_pk_bf16(b[2], b[3]); return w; }
;     __device__ __forceinline__ void operator()(const f32x4 (&acc)[2][2][4][2], const Unit& u, int wr, int wc, int fr, int fq) const {
;     ...
;         for (int ai = 0; ai < 2; ++ai)
; #pragma unroll
;             for (int m = 0; m < 4; ++m) {
;                 const int row = u.pm * BM + ai * HALF + wr * 64 + m * 16 + fr;
;                 const float rstd = rs[ai][m];
;                 const f32x4 a0 = silu4(acc[ai][0][m][0] * rstd) * (acc[ai][1][m][0] * rstd);
;                 const f32x4 a1 = silu4(acc[ai][0][m][1] * rstd) * (acc[ai][1][m][1] * rstd);
;                 *(u32x4*)(ACT + (size_t)row * 2816 + col0) = pack8(a0, a1);
;             }
	v_cvt_pk_bf16_f32 v96, v100, v101
	v_mad_i64_i32 v[100:101], s[38:39], v166, s56, v[112:113]
	v_pk_mul_f32 v[92:93], v[92:93], v[172:173] op_sel_hi:[1,0]
	v_cvt_pk_bf16_f32 v97, v102, v103
	v_cvt_pk_bf16_f32 v98, v98, v99
	v_cvt_pk_bf16_f32 v99, v106, v107
	v_pk_mul_f32 v[94:95], v[94:95], v[172:173] op_sel_hi:[1,0]
	v_mul_f32_e32 v102, 0xbfb8aa3b, v92
	v_mul_f32_e32 v103, 0xbfb8aa3b, v93
	v_lshl_add_u64 v[100:101], v[100:101], 0, v[114:115]
	v_pk_mul_f32 v[88:89], v[88:89], v[172:173] op_sel_hi:[1,0]
	v_pk_mul_f32 v[90:91], v[90:91], v[172:173] op_sel_hi:[1,0]
	v_exp_f32_e32 v102, v102
	v_exp_f32_e32 v103, v103
	v_mul_f32_e32 v104, 0xbfb8aa3b, v94
	v_mul_f32_e32 v105, 0xbfb8aa3b, v95
	global_store_dwordx4 v[100:101], v[96:99], off nt
	v_exp_f32_e32 v104, v104
	v_exp_f32_e32 v105, v105
	v_mul_f32_e32 v96, 0xbfb8aa3b, v88
	v_mul_f32_e32 v97, 0xbfb8aa3b, v89
	v_mul_f32_e32 v98, 0xbfb8aa3b, v90
	v_mul_f32_e32 v99, 0xbfb8aa3b, v91
	v_exp_f32_e32 v96, v96
	v_exp_f32_e32 v97, v97
	v_exp_f32_e32 v98, v98
	v_exp_f32_e32 v99, v99
	v_add_f32_e32 v102, 1.0, v102
	v_add_f32_e32 v103, 1.0, v103
	v_rcp_f32_e32 v102, v102
	v_rcp_f32_e32 v103, v103
	v_add_f32_e32 v104, 1.0, v104
	v_add_f32_e32 v105, 1.0, v105
	v_add_f32_e32 v96, 1.0, v96
	v_add_f32_e32 v97, 1.0, v97
	v_add_f32_e32 v98, 1.0, v98
	v_add_f32_e32 v99, 1.0, v99
	v_rcp_f32_e32 v104, v104
	v_rcp_f32_e32 v105, v105
	v_rcp_f32_e32 v96, v96
	v_rcp_f32_e32 v97, v97
	v_rcp_f32_e32 v98, v98
	v_rcp_f32_e32 v99, v99
	v_pk_mul_f32 v[92:93], v[92:93], v[102:103]
	v_pk_mul_f32 v[84:85], v[84:85], v[172:173] op_sel_hi:[1,0]
	v_pk_mul_f32 v[94:95], v[94:95], v[104:105]
	v_pk_mul_f32 v[86:87], v[86:87], v[172:173] op_sel_hi:[1,0]
	v_pk_mul_f32 v[84:85], v[84:85], v[92:93]
	v_pk_mul_f32 v[88:89], v[88:89], v[96:97]
	v_pk_mul_f32 v[90:91], v[90:91], v[98:99]
	v_pk_mul_f32 v[80:81], v[80:81], v[172:173] op_sel_hi:[1,0]
	v_pk_mul_f32 v[82:83], v[82:83], v[172:173] op_sel_hi:[1,0]
	v_pk_mul_f32 v[86:87], v[86:87], v[94:95]
	v_pk_mul_f32 v[90:91], v[82:83], v[90:91]
	v_pk_mul_f32 v[82:83], v[80:81], v[88:89]
	v_cvt_pk_bf16_f32 v80, v84, v85
	v_mad_i64_i32 v[84:85], s[38:39], v162, s56, v[112:113]
	v_pk_mul_f32 v[76:77], v[76:77], v[168:169] op_sel_hi:[1,0]
	v_cvt_pk_bf16_f32 v81, v86, v87
	v_cvt_pk_bf16_f32 v82, v82, v83
	v_cvt_pk_bf16_f32 v83, v90, v91
	v_pk_mul_f32 v[78:79], v[78:79], v[168:169] op_sel_hi:[1,0]
	v_mul_f32_e32 v86, 0xbfb8aa3b, v76
	v_mul_f32_e32 v87, 0xbfb8aa3b, v77
	v_lshl_add_u64 v[84:85], v[84:85], 0, v[114:115]
	v_pk_mul_f32 v[72:73], v[72:73], v[168:169] op_sel_hi:[1,0]
	v_pk_mul_f32 v[74:75], v[74:75], v[168:169] op_sel_hi:[1,0]
	v_exp_f32_e32 v86, v86
	v_exp_f32_e32 v87, v87
	v_mul_f32_e32 v88, 0xbfb8aa3b, v78
	v_mul_f32_e32 v89, 0xbfb8aa3b, v79
	global_store_dwordx4 v[84:85], v[80:83], off nt
	v_exp_f32_e32 v88, v88
	v_exp_f32_e32 v89, v89
	v_mul_f32_e32 v80, 0xbfb8aa3b, v72
	v_mul_f32_e32 v81, 0xbfb8aa3b, v73
	v_mul_f32_e32 v82, 0xbfb8aa3b, v74
	v_mul_f32_e32 v83, 0xbfb8aa3b, v75
	v_exp_f32_e32 v80, v80
	v_exp_f32_e32 v81, v81
	v_exp_f32_e32 v82, v82
	v_exp_f32_e32 v83, v83
	v_add_f32_e32 v86, 1.0, v86
	v_add_f32_e32 v87, 1.0, v87
	v_rcp_f32_e32 v86, v86
	v_rcp_f32_e32 v87, v87
	v_add_f32_e32 v88, 1.0, v88
	v_add_f32_e32 v89, 1.0, v89
	v_add_f32_e32 v80, 1.0, v80
	v_add_f32_e32 v81, 1.0, v81
	v_add_f32_e32 v82, 1.0, v82
	v_add_f32_e32 v83, 1.0, v83
	v_rcp_f32_e32 v88, v88
	v_rcp_f32_e32 v89, v89
	v_rcp_f32_e32 v80, v80
	v_rcp_f32_e32 v81, v81
	v_rcp_f32_e32 v82, v82
	v_rcp_f32_e32 v83, v83
	v_pk_mul_f32 v[76:77], v[76:77], v[86:87]
	v_pk_mul_f32 v[68:69], v[68:69], v[168:169] op_sel_hi:[1,0]
	v_pk_mul_f32 v[78:79], v[78:79], v[88:89]
	v_pk_mul_f32 v[70:71], v[70:71], v[168:169] op_sel_hi:[1,0]
	v_pk_mul_f32 v[68:69], v[68:69], v[76:77]
	v_pk_mul_f32 v[72:73], v[72:73], v[80:81]
	v_pk_mul_f32 v[74:75], v[74:75], v[82:83]
	v_pk_mul_f32 v[64:65], v[64:65], v[168:169] op_sel_hi:[1,0]
	v_pk_mul_f32 v[66:67], v[66:67], v[168:169] op_sel_hi:[1,0]
	v_pk_mul_f32 v[70:71], v[70:71], v[78:79]
	v_pk_mul_f32 v[74:75], v[66:67], v[74:75]
	v_pk_mul_f32 v[66:67], v[64:65], v[72:73]
	v_cvt_pk_bf16_f32 v64, v68, v69
	v_mad_i64_i32 v[68:69], s[38:39], v158, s56, v[112:113]
	v_pk_mul_f32 v[60:61], v[60:61], v[164:165] op_sel_hi:[1,0]
	v_cvt_pk_bf16_f32 v65, v70, v71
	v_cvt_pk_bf16_f32 v66, v66, v67
	v_cvt_pk_bf16_f32 v67, v74, v75
	v_pk_mul_f32 v[62:63], v[62:63], v[164:165] op_sel_hi:[1,0]
	v_mul_f32_e32 v70, 0xbfb8aa3b, v60
	v_mul_f32_e32 v71, 0xbfb8aa3b, v61
	v_lshl_add_u64 v[68:69], v[68:69], 0, v[114:115]
	v_pk_mul_f32 v[56:57], v[56:57], v[164:165] op_sel_hi:[1,0]
	v_pk_mul_f32 v[58:59], v[58:59], v[164:165] op_sel_hi:[1,0]
	v_exp_f32_e32 v70, v70
	v_exp_f32_e32 v71, v71
	v_mul_f32_e32 v72, 0xbfb8aa3b, v62
	v_mul_f32_e32 v73, 0xbfb8aa3b, v63
	global_store_dwordx4 v[68:69], v[64:67], off nt
	v_exp_f32_e32 v72, v72
	v_exp_f32_e32 v73, v73
	v_mul_f32_e32 v64, 0xbfb8aa3b, v56
	v_mul_f32_e32 v65, 0xbfb8aa3b, v57
	v_mul_f32_e32 v66, 0xbfb8aa3b, v58
	v_mul_f32_e32 v67, 0xbfb8aa3b, v59
	v_exp_f32_e32 v64, v64
	v_exp_f32_e32 v65, v65
	v_exp_f32_e32 v66, v66
	v_exp_f32_e32 v67, v67
	v_add_f32_e32 v70, 1.0, v70
	v_add_f32_e32 v71, 1.0, v71
	v_rcp_f32_e32 v70, v70
	v_rcp_f32_e32 v71, v71
	v_add_f32_e32 v72, 1.0, v72
	v_add_f32_e32 v73, 1.0, v73
	v_add_f32_e32 v64, 1.0, v64
	v_add_f32_e32 v65, 1.0, v65
	v_add_f32_e32 v66, 1.0, v66
	v_add_f32_e32 v67, 1.0, v67
	v_rcp_f32_e32 v72, v72
	v_rcp_f32_e32 v73, v73
	v_rcp_f32_e32 v64, v64
	v_rcp_f32_e32 v65, v65
	v_rcp_f32_e32 v66, v66
	v_rcp_f32_e32 v67, v67
	v_pk_mul_f32 v[60:61], v[60:61], v[70:71]
	v_pk_mul_f32 v[52:53], v[52:53], v[164:165] op_sel_hi:[1,0]
; __device__ __forceinline__ f32x4 silu4(f32x4 v) { return (f32x4){silu_f(v[0]), silu_f(v[1]), silu_f(v[2]), silu_f(v[3])}; }
; __device__ __forceinline__ u32x4 pack8(f32x4 a, f32x4 b) { u32x4 w; w.x = cvt_pk_bf16(a[0], a[1]); w.y = cvt_pk_bf16(a[2], a[3]); w.z = cvt_pk_bf16(b[0], b[1]); w.w = cvt_pk_bf16(b[2], b[3]); return w; }
;     __device__ __forceinline__ void operator()(const f32x4 (&acc)[2][2][4][2], const Unit& u, int wr, int wc, int fr, int fq) const {
;     ...
;         for (int ai = 0; ai < 2; ++ai)
; #pragma unroll
;             for (int m = 0; m < 4; ++m) {
;                 const int row = u.pm * BM + ai * HALF + wr * 64 + m * 16 + fr;
;                 const float rstd = rs[ai][m];
;                 const f32x4 a0 = silu4(acc[ai][0][m][0] * rstd) * (acc[ai][1][m][0] * rstd);
;                 const f32x4 a1 = silu4(acc[ai][0][m][1] * rstd) * (acc[ai][1][m][1] * rstd);
;                 *(u32x4*)(ACT + (size_t)row * 2816 + col0) = pack8(a0, a1);
;             }
	v_pk_mul_f32 v[62:63], v[62:63], v[72:73]
	v_pk_mul_f32 v[54:55], v[54:55], v[164:165] op_sel_hi:[1,0]
	v_pk_mul_f32 v[52:53], v[52:53], v[60:61]
	v_pk_mul_f32 v[56:57], v[56:57], v[64:65]
	v_pk_mul_f32 v[58:59], v[58:59], v[66:67]
	v_pk_mul_f32 v[48:49], v[48:49], v[164:165] op_sel_hi:[1,0]
	v_pk_mul_f32 v[50:51], v[50:51], v[164:165] op_sel_hi:[1,0]
	v_pk_mul_f32 v[54:55], v[54:55], v[62:63]
	v_pk_mul_f32 v[58:59], v[50:51], v[58:59]
	v_pk_mul_f32 v[50:51], v[48:49], v[56:57]
	v_cvt_pk_bf16_f32 v48, v52, v53
	v_mad_i64_i32 v[52:53], s[38:39], v154, s56, v[112:113]
	v_pk_mul_f32 v[44:45], v[44:45], v[160:161] op_sel_hi:[1,0]
	v_cvt_pk_bf16_f32 v49, v54, v55
	v_cvt_pk_bf16_f32 v50, v50, v51
	v_cvt_pk_bf16_f32 v51, v58, v59
	v_pk_mul_f32 v[46:47], v[46:47], v[160:161] op_sel_hi:[1,0]
	v_mul_f32_e32 v54, 0xbfb8aa3b, v44
	v_mul_f32_e32 v55, 0xbfb8aa3b, v45
	v_lshl_add_u64 v[52:53], v[52:53], 0, v[114:115]
	v_pk_mul_f32 v[40:41], v[40:41], v[160:161] op_sel_hi:[1,0]
	v_pk_mul_f32 v[42:43], v[42:43], v[160:161] op_sel_hi:[1,0]
	v_exp_f32_e32 v54, v54
	v_exp_f32_e32 v55, v55
	v_mul_f32_e32 v56, 0xbfb8aa3b, v46
	v_mul_f32_e32 v57, 0xbfb8aa3b, v47
	global_store_dwordx4 v[52:53], v[48:51], off nt
	v_exp_f32_e32 v56, v56
	v_exp_f32_e32 v57, v57
	v_mul_f32_e32 v48, 0xbfb8aa3b, v40
	v_mul_f32_e32 v49, 0xbfb8aa3b, v41
	v_mul_f32_e32 v50, 0xbfb8aa3b, v42
	v_mul_f32_e32 v51, 0xbfb8aa3b, v43
	v_exp_f32_e32 v48, v48
	v_exp_f32_e32 v49, v49
	v_exp_f32_e32 v50, v50
	v_exp_f32_e32 v51, v51
	v_add_f32_e32 v54, 1.0, v54
	v_add_f32_e32 v55, 1.0, v55
	v_rcp_f32_e32 v54, v54
	v_rcp_f32_e32 v55, v55
	v_add_f32_e32 v56, 1.0, v56
	v_add_f32_e32 v57, 1.0, v57
	v_add_f32_e32 v48, 1.0, v48
	v_add_f32_e32 v49, 1.0, v49
	v_add_f32_e32 v50, 1.0, v50
	v_add_f32_e32 v51, 1.0, v51
	v_rcp_f32_e32 v56, v56
	v_rcp_f32_e32 v57, v57
	v_rcp_f32_e32 v48, v48
	v_rcp_f32_e32 v49, v49
	v_rcp_f32_e32 v50, v50
	v_rcp_f32_e32 v51, v51
	v_pk_mul_f32 v[44:45], v[44:45], v[54:55]
	v_pk_mul_f32 v[36:37], v[36:37], v[160:161] op_sel_hi:[1,0]
	v_pk_mul_f32 v[46:47], v[46:47], v[56:57]
	v_pk_mul_f32 v[38:39], v[38:39], v[160:161] op_sel_hi:[1,0]
	v_pk_mul_f32 v[36:37], v[36:37], v[44:45]
	v_pk_mul_f32 v[40:41], v[40:41], v[48:49]
	v_pk_mul_f32 v[42:43], v[42:43], v[50:51]
	v_pk_mul_f32 v[32:33], v[32:33], v[160:161] op_sel_hi:[1,0]
	v_pk_mul_f32 v[34:35], v[34:35], v[160:161] op_sel_hi:[1,0]
	v_pk_mul_f32 v[38:39], v[38:39], v[46:47]
	v_pk_mul_f32 v[42:43], v[34:35], v[42:43]
	v_pk_mul_f32 v[34:35], v[32:33], v[40:41]
	v_cvt_pk_bf16_f32 v32, v36, v37
	v_mad_i64_i32 v[36:37], s[38:39], v150, s56, v[112:113]
	v_pk_mul_f32 v[28:29], v[28:29], v[156:157] op_sel_hi:[1,0]
	v_cvt_pk_bf16_f32 v33, v38, v39
	v_cvt_pk_bf16_f32 v34, v34, v35
	v_cvt_pk_bf16_f32 v35, v42, v43
	v_pk_mul_f32 v[30:31], v[30:31], v[156:157] op_sel_hi:[1,0]
	v_mul_f32_e32 v38, 0xbfb8aa3b, v28
	v_mul_f32_e32 v39, 0xbfb8aa3b, v29
	v_lshl_add_u64 v[36:37], v[36:37], 0, v[114:115]
	v_pk_mul_f32 v[24:25], v[24:25], v[156:157] op_sel_hi:[1,0]
	v_pk_mul_f32 v[26:27], v[26:27], v[156:157] op_sel_hi:[1,0]
	v_exp_f32_e32 v38, v38
	v_exp_f32_e32 v39, v39
	v_mul_f32_e32 v40, 0xbfb8aa3b, v30
	v_mul_f32_e32 v41, 0xbfb8aa3b, v31
	global_store_dwordx4 v[36:37], v[32:35], off nt
	v_exp_f32_e32 v40, v40
	v_exp_f32_e32 v41, v41
	v_mul_f32_e32 v32, 0xbfb8aa3b, v24
	v_mul_f32_e32 v33, 0xbfb8aa3b, v25
	v_mul_f32_e32 v34, 0xbfb8aa3b, v26
	v_mul_f32_e32 v35, 0xbfb8aa3b, v27
	v_exp_f32_e32 v32, v32
	v_exp_f32_e32 v33, v33
	v_exp_f32_e32 v34, v34
	v_exp_f32_e32 v35, v35
	v_add_f32_e32 v38, 1.0, v38
	v_add_f32_e32 v39, 1.0, v39
	v_rcp_f32_e32 v38, v38
	v_rcp_f32_e32 v39, v39
	v_add_f32_e32 v40, 1.0, v40
	v_add_f32_e32 v41, 1.0, v41
	v_add_f32_e32 v32, 1.0, v32
	v_add_f32_e32 v33, 1.0, v33
	v_add_f32_e32 v34, 1.0, v34
	v_add_f32_e32 v35, 1.0, v35
	v_rcp_f32_e32 v40, v40
	v_rcp_f32_e32 v41, v41
	v_rcp_f32_e32 v32, v32
	v_rcp_f32_e32 v33, v33
	v_rcp_f32_e32 v34, v34
	v_rcp_f32_e32 v35, v35
	v_pk_mul_f32 v[28:29], v[28:29], v[38:39]
	v_pk_mul_f32 v[20:21], v[20:21], v[156:157] op_sel_hi:[1,0]
	v_pk_mul_f32 v[30:31], v[30:31], v[40:41]
	v_pk_mul_f32 v[22:23], v[22:23], v[156:157] op_sel_hi:[1,0]
	v_pk_mul_f32 v[20:21], v[20:21], v[28:29]
	v_pk_mul_f32 v[24:25], v[24:25], v[32:33]
	v_pk_mul_f32 v[26:27], v[26:27], v[34:35]
	v_pk_mul_f32 v[16:17], v[16:17], v[156:157] op_sel_hi:[1,0]
	v_pk_mul_f32 v[18:19], v[18:19], v[156:157] op_sel_hi:[1,0]
	v_pk_mul_f32 v[22:23], v[22:23], v[30:31]
	v_pk_mul_f32 v[26:27], v[18:19], v[26:27]
	v_pk_mul_f32 v[18:19], v[16:17], v[24:25]
	v_cvt_pk_bf16_f32 v16, v20, v21
	v_mad_i64_i32 v[20:21], s[38:39], v148, s56, v[112:113]
	v_pk_mul_f32 v[12:13], v[12:13], v[152:153] op_sel_hi:[1,0]
	v_cvt_pk_bf16_f32 v17, v22, v23
	v_cvt_pk_bf16_f32 v18, v18, v19
	v_cvt_pk_bf16_f32 v19, v26, v27
	v_lshl_add_u64 v[20:21], v[20:21], 0, v[114:115]
	v_mul_f32_e32 v22, 0xbfb8aa3b, v12
	v_mul_f32_e32 v23, 0xbfb8aa3b, v13
	v_pk_mul_f32 v[8:9], v[8:9], v[152:153] op_sel_hi:[1,0]
	v_pk_mul_f32 v[10:11], v[10:11], v[152:153] op_sel_hi:[1,0]
	v_exp_f32_e32 v22, v22
	v_exp_f32_e32 v23, v23
	global_store_dwordx4 v[20:21], v[16:19], off nt
	v_pk_mul_f32 v[14:15], v[14:15], v[152:153] op_sel_hi:[1,0]
	v_add_f32_e32 v22, 1.0, v22
	v_mul_f32_e32 v16, 0xbfb8aa3b, v8
	v_mul_f32_e32 v17, 0xbfb8aa3b, v9
	v_mul_f32_e32 v18, 0xbfb8aa3b, v10
	v_mul_f32_e32 v19, 0xbfb8aa3b, v11
	v_exp_f32_e32 v16, v16
	v_exp_f32_e32 v17, v17
	v_exp_f32_e32 v18, v18
	v_exp_f32_e32 v19, v19
	v_mul_f32_e32 v24, 0xbfb8aa3b, v14
	v_mul_f32_e32 v25, 0xbfb8aa3b, v15
	v_exp_f32_e32 v24, v24
	v_exp_f32_e32 v25, v25
	v_add_f32_e32 v23, 1.0, v23
	v_rcp_f32_e32 v22, v22
	v_rcp_f32_e32 v23, v23
	v_add_f32_e32 v16, 1.0, v16
	v_add_f32_e32 v17, 1.0, v17
	v_add_f32_e32 v18, 1.0, v18
	v_add_f32_e32 v19, 1.0, v19
	v_rcp_f32_e32 v16, v16
	v_rcp_f32_e32 v17, v17
	v_rcp_f32_e32 v18, v18
	v_rcp_f32_e32 v19, v19
	v_add_f32_e32 v24, 1.0, v24
	v_add_f32_e32 v25, 1.0, v25
	v_rcp_f32_e32 v24, v24
	v_rcp_f32_e32 v25, v25
	v_pk_mul_f32 v[12:13], v[12:13], v[22:23]
	v_pk_mul_f32 v[4:5], v[4:5], v[152:153] op_sel_hi:[1,0]
	v_pk_mul_f32 v[8:9], v[8:9], v[16:17]
	v_pk_mul_f32 v[4:5], v[4:5], v[12:13]
	v_pk_mul_f32 v[10:11], v[10:11], v[18:19]
	v_pk_mul_f32 v[0:1], v[0:1], v[152:153] op_sel_hi:[1,0]
	v_pk_mul_f32 v[2:3], v[2:3], v[152:153] op_sel_hi:[1,0]
	v_pk_mul_f32 v[14:15], v[14:15], v[24:25]
	v_pk_mul_f32 v[10:11], v[2:3], v[10:11]
	v_pk_mul_f32 v[2:3], v[0:1], v[8:9]
	v_cvt_pk_bf16_f32 v0, v4, v5
	v_mad_i64_i32 v[4:5], s[38:39], v146, s56, v[112:113]
	v_pk_mul_f32 v[6:7], v[6:7], v[152:153] op_sel_hi:[1,0]
	v_lshl_add_u64 v[4:5], v[4:5], 0, v[114:115]
	v_pk_mul_f32 v[6:7], v[6:7], v[14:15]
	s_nop 0
	v_cvt_pk_bf16_f32 v1, v6, v7
	v_cvt_pk_bf16_f32 v2, v2, v3
	v_cvt_pk_bf16_f32 v3, v10, v11
	global_store_dwordx4 v[4:5], v[0:3], off nt
	s_cbranch_vccnz .LBB0_516
	s_andn2_b64 vcc, exec, s[12:13]
	s_cbranch_vccnz .LBB0_515
	s_barrier
	s_branch .LBB0_515

; __device__ __forceinline__ float row_part(const float* ss, int row, int fq) { const f32x4 a = ((const f32x4*)(ss + (size_t)row * 16))[fq]; return (a[0] + a[1]) + (a[2] + a[3]); }
; __device__ __forceinline__ float row_finish(float t) { t += shx(t, 16); t += shx(t, 32); return __builtin_amdgcn_rsqf(t * (1.0f / 1024.0f) + RMS_EPS); }
;     __device__ __forceinline__ void operator()(const f32x4 (&acc)[2][2][4][2], const Unit& u, int wr, int wc, int fr, int fq) const {
;         const int col0 = u.pn * 128 + 32 * wc + 8 * fq;
;         float rs[2][4];
; #pragma unroll
;         for (int ai = 0; ai < 2; ++ai)
; #pragma unroll
;             for (int m = 0; m < 4; ++m) rs[ai][m] = row_part(ss, u.pm * BM + ai * HALF + wr * 64 + m * 16 + fr, fq);
; #pragma unroll
;         for (int ai = 0; ai < 2; ++ai)
; #pragma unroll
;             for (int m = 0; m < 4; ++m) rs[ai][m] = row_finish(rs[ai][m]);
.LBB0_999:
	v_lshl_add_u32 v168, s48, 8, v155
	v_ashrrev_i32_e32 v169, 31, v168
	v_lshlrev_b64 v[146:147], 6, v[168:169]
	v_lshl_add_u64 v[146:147], v[136:137], 0, v[146:147]
	ds_read_b128 v[146:149], v239
	v_or_b32_e32 v164, 16, v168
	v_ashrrev_i32_e32 v165, 31, v164
	v_or_b32_e32 v160, 32, v168
	v_ashrrev_i32_e32 v161, 31, v160
	v_or_b32_e32 v156, 48, v168
	v_ashrrev_i32_e32 v157, 31, v156
	v_add_u32_e32 v152, 0x80, v168
	v_ashrrev_i32_e32 v153, 31, v152
	v_mov_b32_e32 v162, v201
	s_andn2_b64 vcc, exec, s[16:17]
	s_waitcnt lgkmcnt(0)
	v_mov_b32_e32 v150, v147
	v_mov_b32_e32 v151, v148
	v_mov_b32_e32 v147, v149
	v_pk_add_f32 v[146:147], v[150:151], v[146:147]
	s_nop 0
	v_add_f32_e32 v154, v146, v147
	v_lshlrev_b64 v[146:147], 6, v[164:165]
	v_lshl_add_u64 v[146:147], v[136:137], 0, v[146:147]
	ds_read_b128 v[146:149], v239 offset:1024
	s_waitcnt lgkmcnt(0)
	v_mov_b32_e32 v150, v147
	v_mov_b32_e32 v151, v148
	v_mov_b32_e32 v147, v149
	v_pk_add_f32 v[146:147], v[150:151], v[146:147]
	s_nop 0
	v_add_f32_e32 v158, v146, v147
	v_lshlrev_b64 v[146:147], 6, v[160:161]
	v_lshl_add_u64 v[146:147], v[136:137], 0, v[146:147]
	ds_read_b128 v[146:149], v239 offset:2048
	s_waitcnt lgkmcnt(0)
	v_mov_b32_e32 v150, v147
	v_mov_b32_e32 v151, v148
	v_mov_b32_e32 v147, v149
	v_pk_add_f32 v[146:147], v[150:151], v[146:147]
	s_nop 0
	v_add_f32_e32 v161, v146, v147
	v_lshlrev_b64 v[146:147], 6, v[156:157]
	v_lshl_add_u64 v[146:147], v[136:137], 0, v[146:147]
	ds_read_b128 v[146:149], v239 offset:3072
	s_waitcnt lgkmcnt(0)
	v_mov_b32_e32 v150, v147
	v_mov_b32_e32 v151, v148
	v_mov_b32_e32 v147, v149
	v_pk_add_f32 v[146:147], v[150:151], v[146:147]
	s_nop 0
	v_add_f32_e32 v157, v146, v147
	v_lshlrev_b64 v[146:147], 6, v[152:153]
	v_lshl_add_u64 v[146:147], v[136:137], 0, v[146:147]
	ds_read_b128 v[146:149], v239 offset:8192
	s_waitcnt lgkmcnt(0)
	v_mov_b32_e32 v150, v147
	v_mov_b32_e32 v151, v148
	v_mov_b32_e32 v147, v149
	v_pk_add_f32 v[146:147], v[150:151], v[146:147]
	v_add_u32_e32 v150, 0x90, v168
	v_ashrrev_i32_e32 v151, 31, v150
	v_add_f32_e32 v153, v146, v147
	v_lshlrev_b64 v[146:147], 6, v[150:151]
	v_lshl_add_u64 v[146:147], v[136:137], 0, v[146:147]
	ds_read_b128 v[146:149], v239 offset:9216
	s_waitcnt lgkmcnt(0)
	v_mov_b32_e32 v176, v147
	v_mov_b32_e32 v177, v148
	v_mov_b32_e32 v147, v149
	v_add_u32_e32 v148, 0xa0, v168
	v_pk_add_f32 v[146:147], v[176:177], v[146:147]
	v_ashrrev_i32_e32 v149, 31, v148
	v_add_f32_e32 v151, v146, v147
	v_lshlrev_b64 v[146:147], 6, v[148:149]
	v_lshl_add_u64 v[146:147], v[136:137], 0, v[146:147]
	ds_read_b128 v[176:179], v239 offset:10240
	s_waitcnt lgkmcnt(0)
	v_mov_b32_e32 v146, v177
	v_mov_b32_e32 v147, v178
	v_mov_b32_e32 v177, v179
	v_pk_add_f32 v[146:147], v[146:147], v[176:177]
	s_nop 0
	v_add_f32_e32 v149, v146, v147
	v_add_u32_e32 v146, 0xb0, v168
	v_ashrrev_i32_e32 v147, 31, v146
	v_lshlrev_b64 v[176:177], 6, v[146:147]
	v_lshl_add_u64 v[176:177], v[136:137], 0, v[176:177]
	ds_read_b128 v[176:179], v239 offset:11264
	s_waitcnt lgkmcnt(0)
	v_mov_b32_e32 v180, v177
	v_lshlrev_b32_e32 v162, 2, v162
	v_xor_b32_e32 v162, 64, v162
	v_mov_b32_e32 v162, v154
	s_nop 1
	v_permlane16_swap_b32_e32 v162, v154
	v_mov_b32_e32 v181, v178
	v_mov_b32_e32 v177, v179
	v_pk_add_f32 v[176:177], v[180:181], v[176:177]
	v_lshl_or_b32 v178, s49, 7, v163
	s_waitcnt lgkmcnt(0)
	v_add_f32_e32 v154, v154, v162
	v_mov_b32_e32 v162, v201
	v_add_f32_e32 v147, v176, v177
	v_lshlrev_b32_e32 v162, 2, v162
	v_xor_b32_e32 v162, 0x80, v162
	v_mov_b32_e32 v162, v154
	s_nop 1
	v_permlane32_swap_b32_e32 v162, v154
	v_ashrrev_i32_e32 v179, 31, v178
	s_mov_b64 s[48:49], -1
	s_waitcnt lgkmcnt(0)
	v_add_f32_e32 v154, v154, v162
	v_fmamk_f32 v154, v154, 0x3a800000, v175
	v_rsq_f32_e32 v174, v154
	v_mov_b32_e32 v154, v201
	v_pk_mul_f32 v[124:125], v[124:125], v[174:175] op_sel_hi:[1,0]
	v_lshlrev_b32_e32 v154, 2, v154
	v_xor_b32_e32 v154, 64, v154
	v_mov_b32_e32 v154, v158
	s_nop 1
	v_permlane16_swap_b32_e32 v154, v158
	v_pk_mul_f32 v[126:127], v[126:127], v[174:175] op_sel_hi:[1,0]
	v_pk_mul_f32 v[116:117], v[116:117], v[174:175] op_sel_hi:[1,0]
	v_pk_mul_f32 v[120:121], v[120:121], v[174:175] op_sel_hi:[1,0]
	v_pk_mul_f32 v[118:119], v[118:119], v[174:175] op_sel_hi:[1,0]
	s_waitcnt lgkmcnt(0)
	v_add_f32_e32 v154, v158, v154
	v_mov_b32_e32 v158, v201
	v_pk_mul_f32 v[122:123], v[122:123], v[174:175] op_sel_hi:[1,0]
	v_lshlrev_b32_e32 v158, 2, v158
	v_xor_b32_e32 v158, 0x80, v158
	v_mov_b32_e32 v158, v154
	s_nop 1
	v_permlane32_swap_b32_e32 v158, v154
	v_pk_mul_f32 v[112:113], v[112:113], v[174:175] op_sel_hi:[1,0]
	v_pk_mul_f32 v[114:115], v[114:115], v[174:175] op_sel_hi:[1,0]
	s_waitcnt lgkmcnt(0)
	v_add_f32_e32 v154, v154, v158
	v_fmamk_f32 v154, v154, 0x3a800000, v175
	v_rsq_f32_e32 v176, v154
	v_mov_b32_e32 v154, v201
	v_mov_b32_e32 v158, v201
	v_lshlrev_b32_e32 v154, 2, v154
	v_xor_b32_e32 v154, 64, v154
	v_mov_b32_e32 v154, v161
	s_nop 1
	v_permlane16_swap_b32_e32 v154, v161
	v_pk_mul_f32 v[110:111], v[110:111], v[176:177] op_sel_hi:[1,0]
	v_lshlrev_b32_e32 v158, 2, v158
	v_xor_b32_e32 v158, 0x80, v158
	s_waitcnt lgkmcnt(0)
	v_add_f32_e32 v154, v161, v154
	v_mov_b32_e32 v158, v154
	s_nop 1
	v_permlane32_swap_b32_e32 v158, v154
	v_pk_mul_f32 v[108:109], v[108:109], v[176:177] op_sel_hi:[1,0]
	v_pk_mul_f32 v[100:101], v[100:101], v[176:177] op_sel_hi:[1,0]
	v_pk_mul_f32 v[102:103], v[102:103], v[176:177] op_sel_hi:[1,0]
	v_pk_mul_f32 v[106:107], v[106:107], v[176:177] op_sel_hi:[1,0]
	s_waitcnt lgkmcnt(0)
; __device__ __forceinline__ float row_finish(float t) { t += shx(t, 16); t += shx(t, 32); return __builtin_amdgcn_rsqf(t * (1.0f / 1024.0f) + RMS_EPS); }
; __device__ __forceinline__ f32x4 silu4(f32x4 v) { return (f32x4){silu_f(v[0]), silu_f(v[1]), silu_f(v[2]), silu_f(v[3])}; }
;     __device__ __forceinline__ void operator()(const f32x4 (&acc)[2][2][4][2], const Unit& u, int wr, int wc, int fr, int fq) const {
;     ...
;         for (int ai = 0; ai < 2; ++ai)
; #pragma unroll
;             for (int m = 0; m < 4; ++m) rs[ai][m] = row_finish(rs[ai][m]);
; #pragma unroll
;         for (int ai = 0; ai < 2; ++ai)
; #pragma unroll
;             for (int m = 0; m < 4; ++m) {
;                 const int row = u.pm * BM + ai * HALF + wr * 64 + m * 16 + fr;
;                 const float rstd = rs[ai][m];
;                 const f32x4 a0 = silu4(acc[ai][0][m][0] * rstd) * (acc[ai][1][m][0] * rstd);
;                 const f32x4 a1 = silu4(acc[ai][0][m][1] * rstd) * (acc[ai][1][m][1] * rstd);
	v_add_f32_e32 v154, v154, v158
	v_fmamk_f32 v154, v154, 0x3a800000, v175
	v_rsq_f32_e32 v172, v154
	v_mov_b32_e32 v154, v201
	v_pk_mul_f32 v[104:105], v[104:105], v[176:177] op_sel_hi:[1,0]
	v_lshlrev_b32_e32 v154, 2, v154
	v_xor_b32_e32 v154, 64, v154
	v_mov_b32_e32 v154, v157
	s_nop 1
	v_permlane16_swap_b32_e32 v154, v157
	v_pk_mul_f32 v[96:97], v[96:97], v[176:177] op_sel_hi:[1,0]
	v_pk_mul_f32 v[98:99], v[98:99], v[176:177] op_sel_hi:[1,0]
	v_pk_mul_f32 v[94:95], v[94:95], v[172:173] op_sel_hi:[1,0]
	v_pk_mul_f32 v[92:93], v[92:93], v[172:173] op_sel_hi:[1,0]
	s_waitcnt lgkmcnt(0)
	v_add_f32_e32 v154, v157, v154
	v_mov_b32_e32 v157, v201
	v_pk_mul_f32 v[84:85], v[84:85], v[172:173] op_sel_hi:[1,0]
	v_lshlrev_b32_e32 v157, 2, v157
	v_xor_b32_e32 v157, 0x80, v157
	v_mov_b32_e32 v157, v154
	s_nop 1
	v_permlane32_swap_b32_e32 v157, v154
	v_pk_mul_f32 v[86:87], v[86:87], v[172:173] op_sel_hi:[1,0]
	v_pk_mul_f32 v[90:91], v[90:91], v[172:173] op_sel_hi:[1,0]
	v_pk_mul_f32 v[88:89], v[88:89], v[172:173] op_sel_hi:[1,0]
	v_pk_mul_f32 v[80:81], v[80:81], v[172:173] op_sel_hi:[1,0]
	s_waitcnt lgkmcnt(0)
	v_add_f32_e32 v154, v154, v157
	v_fmamk_f32 v154, v154, 0x3a800000, v175
	v_rsq_f32_e32 v170, v154
	v_mov_b32_e32 v154, v201
	v_pk_mul_f32 v[82:83], v[82:83], v[172:173] op_sel_hi:[1,0]
	v_lshlrev_b32_e32 v154, 2, v154
	v_xor_b32_e32 v154, 64, v154
	v_mov_b32_e32 v154, v153
	s_nop 1
	v_permlane16_swap_b32_e32 v154, v153
	v_pk_mul_f32 v[78:79], v[78:79], v[170:171] op_sel_hi:[1,0]
	v_pk_mul_f32 v[76:77], v[76:77], v[170:171] op_sel_hi:[1,0]
	v_pk_mul_f32 v[68:69], v[68:69], v[170:171] op_sel_hi:[1,0]
	v_pk_mul_f32 v[70:71], v[70:71], v[170:171] op_sel_hi:[1,0]
	s_waitcnt lgkmcnt(0)
	v_add_f32_e32 v153, v153, v154
	v_mov_b32_e32 v154, v201
	v_pk_mul_f32 v[74:75], v[74:75], v[170:171] op_sel_hi:[1,0]
	v_lshlrev_b32_e32 v154, 2, v154
	v_xor_b32_e32 v154, 0x80, v154
	v_mov_b32_e32 v154, v153
	s_nop 1
	v_permlane32_swap_b32_e32 v154, v153
	v_pk_mul_f32 v[72:73], v[72:73], v[170:171] op_sel_hi:[1,0]
	v_pk_mul_f32 v[64:65], v[64:65], v[170:171] op_sel_hi:[1,0]
	v_pk_mul_f32 v[66:67], v[66:67], v[170:171] op_sel_hi:[1,0]
	s_waitcnt lgkmcnt(0)
	v_add_f32_e32 v153, v153, v154
	v_fmamk_f32 v153, v153, 0x3a800000, v175
	v_rsq_f32_e32 v166, v153
	v_mov_b32_e32 v153, v201
	v_pk_mul_f32 v[62:63], v[62:63], v[166:167] op_sel_hi:[1,0]
	v_lshlrev_b32_e32 v153, 2, v153
	v_xor_b32_e32 v153, 64, v153
	v_mov_b32_e32 v153, v151
	s_nop 1
	v_permlane16_swap_b32_e32 v153, v151
	v_pk_mul_f32 v[60:61], v[60:61], v[166:167] op_sel_hi:[1,0]
	v_pk_mul_f32 v[52:53], v[52:53], v[166:167] op_sel_hi:[1,0]
	v_pk_mul_f32 v[54:55], v[54:55], v[166:167] op_sel_hi:[1,0]
	v_pk_mul_f32 v[58:59], v[58:59], v[166:167] op_sel_hi:[1,0]
	s_waitcnt lgkmcnt(0)
	v_add_f32_e32 v151, v151, v153
	v_mov_b32_e32 v153, v201
	v_pk_mul_f32 v[56:57], v[56:57], v[166:167] op_sel_hi:[1,0]
	v_lshlrev_b32_e32 v153, 2, v153
	v_xor_b32_e32 v153, 0x80, v153
	v_mov_b32_e32 v153, v151
	s_nop 1
	v_permlane32_swap_b32_e32 v153, v151
	v_pk_mul_f32 v[48:49], v[48:49], v[166:167] op_sel_hi:[1,0]
	v_pk_mul_f32 v[50:51], v[50:51], v[166:167] op_sel_hi:[1,0]
	s_waitcnt lgkmcnt(0)
	v_add_f32_e32 v151, v151, v153
	v_fmamk_f32 v151, v151, 0x3a800000, v175
	v_rsq_f32_e32 v162, v151
	v_mov_b32_e32 v151, v201
	v_pk_mul_f32 v[46:47], v[46:47], v[162:163] op_sel_hi:[1,0]
	v_lshlrev_b32_e32 v151, 2, v151
	v_xor_b32_e32 v151, 64, v151
	v_mov_b32_e32 v151, v149
	s_nop 1
	v_permlane16_swap_b32_e32 v151, v149
	v_pk_mul_f32 v[44:45], v[44:45], v[162:163] op_sel_hi:[1,0]
	v_pk_mul_f32 v[36:37], v[36:37], v[162:163] op_sel_hi:[1,0]
	v_pk_mul_f32 v[38:39], v[38:39], v[162:163] op_sel_hi:[1,0]
	v_pk_mul_f32 v[42:43], v[42:43], v[162:163] op_sel_hi:[1,0]
	s_waitcnt lgkmcnt(0)
	v_add_f32_e32 v149, v149, v151
	v_mov_b32_e32 v151, v201
	v_pk_mul_f32 v[40:41], v[40:41], v[162:163] op_sel_hi:[1,0]
	v_lshlrev_b32_e32 v151, 2, v151
	v_xor_b32_e32 v151, 0x80, v151
	v_mov_b32_e32 v151, v149
	s_nop 1
	v_permlane32_swap_b32_e32 v151, v149
	v_pk_mul_f32 v[32:33], v[32:33], v[162:163] op_sel_hi:[1,0]
	v_pk_mul_f32 v[34:35], v[34:35], v[162:163] op_sel_hi:[1,0]
	s_waitcnt lgkmcnt(0)
	v_add_f32_e32 v149, v149, v151
	v_fmamk_f32 v149, v149, 0x3a800000, v175
	v_rsq_f32_e32 v158, v149
	v_mov_b32_e32 v149, v201
	v_pk_mul_f32 v[30:31], v[30:31], v[158:159] op_sel_hi:[1,0]
	v_lshlrev_b32_e32 v149, 2, v149
	v_xor_b32_e32 v149, 64, v149
	v_mov_b32_e32 v149, v147
	s_nop 1
	v_permlane16_swap_b32_e32 v149, v147
	v_pk_mul_f32 v[28:29], v[28:29], v[158:159] op_sel_hi:[1,0]
	v_pk_mul_f32 v[20:21], v[20:21], v[158:159] op_sel_hi:[1,0]
	v_pk_mul_f32 v[22:23], v[22:23], v[158:159] op_sel_hi:[1,0]
	v_pk_mul_f32 v[26:27], v[26:27], v[158:159] op_sel_hi:[1,0]
	s_waitcnt lgkmcnt(0)
	v_add_f32_e32 v147, v147, v149
	v_mov_b32_e32 v149, v201
	v_pk_mul_f32 v[24:25], v[24:25], v[158:159] op_sel_hi:[1,0]
	v_lshlrev_b32_e32 v149, 2, v149
	v_xor_b32_e32 v149, 0x80, v149
	v_mov_b32_e32 v149, v147
	s_nop 1
	v_permlane32_swap_b32_e32 v149, v147
	v_pk_mul_f32 v[16:17], v[16:17], v[158:159] op_sel_hi:[1,0]
	v_pk_mul_f32 v[18:19], v[18:19], v[158:159] op_sel_hi:[1,0]
	s_waitcnt lgkmcnt(0)
; __device__ __forceinline__ f32x4 silu4(f32x4 v) { return (f32x4){silu_f(v[0]), silu_f(v[1]), silu_f(v[2]), silu_f(v[3])}; }
; __device__ __forceinline__ u32x4 pack8(f32x4 a, f32x4 b) { u32x4 w; w.x = cvt_pk_bf16(a[0], a[1]); w.y = cvt_pk_bf16(a[2], a[3]); w.z = cvt_pk_bf16(b[0], b[1]); w.w = cvt_pk_bf16(b[2], b[3]); return w; }
;     __device__ __forceinline__ void operator()(const f32x4 (&acc)[2][2][4][2], const Unit& u, int wr, int wc, int fr, int fq) const {
;     ...
;         for (int ai = 0; ai < 2; ++ai)
; #pragma unroll
;             for (int m = 0; m < 4; ++m) {
;                 const int row = u.pm * BM + ai * HALF + wr * 64 + m * 16 + fr;
;                 const float rstd = rs[ai][m];
;                 const f32x4 a0 = silu4(acc[ai][0][m][0] * rstd) * (acc[ai][1][m][0] * rstd);
;                 const f32x4 a1 = silu4(acc[ai][0][m][1] * rstd) * (acc[ai][1][m][1] * rstd);
;                 *(u32x4*)(ACT + (size_t)row * 2816 + col0) = pack8(a0, a1);
;             }
	v_add_f32_e32 v147, v147, v149
	v_fmamk_f32 v147, v147, 0x3a800000, v175
	v_rsq_f32_e32 v154, v147
	v_mul_f32_e32 v147, 0xbfb8aa3b, v124
	v_exp_f32_e32 v147, v147
	v_pk_mul_f32 v[14:15], v[14:15], v[154:155] op_sel_hi:[1,0]
	v_pk_mul_f32 v[12:13], v[12:13], v[154:155] op_sel_hi:[1,0]
	v_add_f32_e32 v147, 1.0, v147
	v_rcp_f32_e32 v180, v147
	v_mul_f32_e32 v147, 0xbfb8aa3b, v125
	v_exp_f32_e32 v147, v147
	v_pk_mul_f32 v[4:5], v[4:5], v[154:155] op_sel_hi:[1,0]
	v_pk_mul_f32 v[6:7], v[6:7], v[154:155] op_sel_hi:[1,0]
	v_pk_mul_f32 v[10:11], v[10:11], v[154:155] op_sel_hi:[1,0]
	v_add_f32_e32 v147, 1.0, v147
	v_rcp_f32_e32 v181, v147
	v_mul_f32_e32 v147, 0xbfb8aa3b, v126
	v_exp_f32_e32 v147, v147
	v_pk_mul_f32 v[8:9], v[8:9], v[154:155] op_sel_hi:[1,0]
	v_pk_mul_f32 v[124:125], v[124:125], v[180:181]
	v_pk_mul_f32 v[0:1], v[0:1], v[154:155] op_sel_hi:[1,0]
	v_add_f32_e32 v147, 1.0, v147
	v_rcp_f32_e32 v182, v147
	v_mul_f32_e32 v147, 0xbfb8aa3b, v127
	v_exp_f32_e32 v147, v147
	v_pk_mul_f32 v[116:117], v[116:117], v[124:125]
	v_mul_f32_e32 v124, 0xbfb8aa3b, v120
	v_mul_f32_e32 v125, 0xbfb8aa3b, v121
	v_add_f32_e32 v147, 1.0, v147
	v_rcp_f32_e32 v183, v147
	v_exp_f32_e32 v124, v124
	v_exp_f32_e32 v125, v125
	v_cvt_pk_bf16_f32 v116, v116, v117
	v_pk_mul_f32 v[126:127], v[126:127], v[182:183]
	v_add_f32_e32 v124, 1.0, v124
	v_pk_mul_f32 v[118:119], v[118:119], v[126:127]
	v_mul_f32_e32 v126, 0xbfb8aa3b, v122
	v_mul_f32_e32 v127, 0xbfb8aa3b, v123
	v_exp_f32_e32 v126, v126
	v_exp_f32_e32 v127, v127
	v_add_f32_e32 v125, 1.0, v125
	v_rcp_f32_e32 v124, v124
	v_rcp_f32_e32 v125, v125
	v_add_f32_e32 v126, 1.0, v126
	v_add_f32_e32 v127, 1.0, v127
	v_rcp_f32_e32 v126, v126
	v_rcp_f32_e32 v127, v127
	v_pk_mul_f32 v[120:121], v[120:121], v[124:125]
	v_cvt_pk_bf16_f32 v117, v118, v119
	v_pk_mul_f32 v[2:3], v[2:3], v[154:155] op_sel_hi:[1,0]
	v_pk_mul_f32 v[122:123], v[122:123], v[126:127]
	v_pk_mul_f32 v[112:113], v[112:113], v[120:121]
	v_pk_mul_f32 v[114:115], v[114:115], v[122:123]
	v_cvt_pk_bf16_f32 v118, v112, v113
	v_mov_b64_e32 v[112:113], s[20:21]
	v_cvt_pk_bf16_f32 v119, v114, v115
	v_mad_i64_i32 v[120:121], s[14:15], v168, s68, v[112:113]
	v_lshlrev_b64 v[114:115], 1, v[178:179]
	v_lshl_add_u64 v[120:121], v[120:121], 0, v[114:115]
	global_store_dwordx4 v[120:121], v[116:119], off nt
	s_nop 1
	v_mul_f32_e32 v116, 0xbfb8aa3b, v108
	v_mul_f32_e32 v117, 0xbfb8aa3b, v109
	v_mul_f32_e32 v118, 0xbfb8aa3b, v110
	v_mul_f32_e32 v119, 0xbfb8aa3b, v111
	v_exp_f32_e32 v116, v116
	v_exp_f32_e32 v117, v117
	v_exp_f32_e32 v118, v118
	v_exp_f32_e32 v119, v119
	v_add_f32_e32 v116, 1.0, v116
	v_add_f32_e32 v117, 1.0, v117
	v_add_f32_e32 v118, 1.0, v118
	v_add_f32_e32 v119, 1.0, v119
	v_rcp_f32_e32 v116, v116
	v_rcp_f32_e32 v117, v117
	v_rcp_f32_e32 v118, v118
	v_rcp_f32_e32 v119, v119
	v_pk_mul_f32 v[108:109], v[108:109], v[116:117]
	s_nop 0
	v_pk_mul_f32 v[100:101], v[100:101], v[108:109]
	v_pk_mul_f32 v[110:111], v[110:111], v[118:119]
	v_mul_f32_e32 v108, 0xbfb8aa3b, v104
	v_pk_mul_f32 v[102:103], v[102:103], v[110:111]
	v_mul_f32_e32 v109, 0xbfb8aa3b, v105
	v_mul_f32_e32 v110, 0xbfb8aa3b, v106
	v_mul_f32_e32 v111, 0xbfb8aa3b, v107
	v_exp_f32_e32 v108, v108
	v_exp_f32_e32 v109, v109
	v_exp_f32_e32 v110, v110
	v_exp_f32_e32 v111, v111
	v_add_f32_e32 v108, 1.0, v108
	v_add_f32_e32 v109, 1.0, v109
	v_add_f32_e32 v110, 1.0, v110
	v_add_f32_e32 v111, 1.0, v111
	v_rcp_f32_e32 v108, v108
	v_rcp_f32_e32 v109, v109
	v_rcp_f32_e32 v110, v110
	v_rcp_f32_e32 v111, v111
	v_pk_mul_f32 v[104:105], v[104:105], v[108:109]
	v_pk_mul_f32 v[106:107], v[106:107], v[110:111]
	s_nop 0
	v_pk_mul_f32 v[106:107], v[98:99], v[106:107]
	v_pk_mul_f32 v[98:99], v[96:97], v[104:105]
	v_cvt_pk_bf16_f32 v96, v100, v101
	v_mad_i64_i32 v[100:101], s[14:15], v164, s68, v[112:113]
	v_cvt_pk_bf16_f32 v97, v102, v103
	v_cvt_pk_bf16_f32 v98, v98, v99
	v_cvt_pk_bf16_f32 v99, v106, v107
	v_lshl_add_u64 v[100:101], v[100:101], 0, v[114:115]
	global_store_dwordx4 v[100:101], v[96:99], off nt
	s_nop 1
	v_mul_f32_e32 v96, 0xbfb8aa3b, v92
	v_mul_f32_e32 v97, 0xbfb8aa3b, v93
	v_mul_f32_e32 v98, 0xbfb8aa3b, v94
	v_mul_f32_e32 v99, 0xbfb8aa3b, v95
	v_exp_f32_e32 v96, v96
	v_exp_f32_e32 v97, v97
	v_exp_f32_e32 v98, v98
	v_exp_f32_e32 v99, v99
	v_add_f32_e32 v96, 1.0, v96
	v_add_f32_e32 v97, 1.0, v97
	v_add_f32_e32 v98, 1.0, v98
	v_add_f32_e32 v99, 1.0, v99
	v_rcp_f32_e32 v96, v96
	v_rcp_f32_e32 v97, v97
	v_rcp_f32_e32 v98, v98
	v_rcp_f32_e32 v99, v99
	v_pk_mul_f32 v[92:93], v[92:93], v[96:97]
	s_nop 0
	v_pk_mul_f32 v[84:85], v[84:85], v[92:93]
	v_pk_mul_f32 v[94:95], v[94:95], v[98:99]
	v_mul_f32_e32 v92, 0xbfb8aa3b, v88
	v_pk_mul_f32 v[86:87], v[86:87], v[94:95]
	v_mul_f32_e32 v93, 0xbfb8aa3b, v89
	v_mul_f32_e32 v94, 0xbfb8aa3b, v90
	v_mul_f32_e32 v95, 0xbfb8aa3b, v91
	v_exp_f32_e32 v92, v92
	v_exp_f32_e32 v93, v93
	v_exp_f32_e32 v94, v94
	v_exp_f32_e32 v95, v95
	v_add_f32_e32 v92, 1.0, v92
	v_add_f32_e32 v93, 1.0, v93
	v_add_f32_e32 v94, 1.0, v94
	v_add_f32_e32 v95, 1.0, v95
	v_rcp_f32_e32 v92, v92
	v_rcp_f32_e32 v93, v93
	v_rcp_f32_e32 v94, v94
	v_rcp_f32_e32 v95, v95
	v_pk_mul_f32 v[88:89], v[88:89], v[92:93]
	v_pk_mul_f32 v[90:91], v[90:91], v[94:95]
	s_nop 0
	v_pk_mul_f32 v[90:91], v[82:83], v[90:91]
	v_pk_mul_f32 v[82:83], v[80:81], v[88:89]
	v_cvt_pk_bf16_f32 v80, v84, v85
	v_mad_i64_i32 v[84:85], s[14:15], v160, s68, v[112:113]
	v_cvt_pk_bf16_f32 v81, v86, v87
	v_cvt_pk_bf16_f32 v82, v82, v83
	v_cvt_pk_bf16_f32 v83, v90, v91
	v_lshl_add_u64 v[84:85], v[84:85], 0, v[114:115]
	global_store_dwordx4 v[84:85], v[80:83], off nt
	s_nop 1
	v_mul_f32_e32 v80, 0xbfb8aa3b, v76
	v_mul_f32_e32 v81, 0xbfb8aa3b, v77
; __device__ __forceinline__ f32x4 silu4(f32x4 v) { return (f32x4){silu_f(v[0]), silu_f(v[1]), silu_f(v[2]), silu_f(v[3])}; }
; __device__ __forceinline__ u32x4 pack8(f32x4 a, f32x4 b) { u32x4 w; w.x = cvt_pk_bf16(a[0], a[1]); w.y = cvt_pk_bf16(a[2], a[3]); w.z = cvt_pk_bf16(b[0], b[1]); w.w = cvt_pk_bf16(b[2], b[3]); return w; }
;     __device__ __forceinline__ void operator()(const f32x4 (&acc)[2][2][4][2], const Unit& u, int wr, int wc, int fr, int fq) const {
;     ...
;         for (int ai = 0; ai < 2; ++ai)
; #pragma unroll
;             for (int m = 0; m < 4; ++m) {
;                 const int row = u.pm * BM + ai * HALF + wr * 64 + m * 16 + fr;
;                 const float rstd = rs[ai][m];
;                 const f32x4 a0 = silu4(acc[ai][0][m][0] * rstd) * (acc[ai][1][m][0] * rstd);
;                 const f32x4 a1 = silu4(acc[ai][0][m][1] * rstd) * (acc[ai][1][m][1] * rstd);
;                 *(u32x4*)(ACT + (size_t)row * 2816 + col0) = pack8(a0, a1);
;             }
	v_mul_f32_e32 v82, 0xbfb8aa3b, v78
	v_mul_f32_e32 v83, 0xbfb8aa3b, v79
	v_exp_f32_e32 v80, v80
	v_exp_f32_e32 v81, v81
	v_exp_f32_e32 v82, v82
	v_exp_f32_e32 v83, v83
	v_add_f32_e32 v80, 1.0, v80
	v_add_f32_e32 v81, 1.0, v81
	v_add_f32_e32 v82, 1.0, v82
	v_add_f32_e32 v83, 1.0, v83
	v_rcp_f32_e32 v80, v80
	v_rcp_f32_e32 v81, v81
	v_rcp_f32_e32 v82, v82
	v_rcp_f32_e32 v83, v83
	v_pk_mul_f32 v[76:77], v[76:77], v[80:81]
	s_nop 0
	v_pk_mul_f32 v[68:69], v[68:69], v[76:77]
	v_pk_mul_f32 v[78:79], v[78:79], v[82:83]
	v_mul_f32_e32 v76, 0xbfb8aa3b, v72
	v_pk_mul_f32 v[70:71], v[70:71], v[78:79]
	v_mul_f32_e32 v77, 0xbfb8aa3b, v73
	v_mul_f32_e32 v78, 0xbfb8aa3b, v74
	v_mul_f32_e32 v79, 0xbfb8aa3b, v75
	v_exp_f32_e32 v76, v76
	v_exp_f32_e32 v77, v77
	v_exp_f32_e32 v78, v78
	v_exp_f32_e32 v79, v79
	v_add_f32_e32 v76, 1.0, v76
	v_add_f32_e32 v77, 1.0, v77
	v_add_f32_e32 v78, 1.0, v78
	v_add_f32_e32 v79, 1.0, v79
	v_rcp_f32_e32 v76, v76
	v_rcp_f32_e32 v77, v77
	v_rcp_f32_e32 v78, v78
	v_rcp_f32_e32 v79, v79
	v_pk_mul_f32 v[72:73], v[72:73], v[76:77]
	v_pk_mul_f32 v[74:75], v[74:75], v[78:79]
	s_nop 0
	v_pk_mul_f32 v[74:75], v[66:67], v[74:75]
	v_pk_mul_f32 v[66:67], v[64:65], v[72:73]
	v_cvt_pk_bf16_f32 v64, v68, v69
	v_mad_i64_i32 v[68:69], s[14:15], v156, s68, v[112:113]
	v_cvt_pk_bf16_f32 v65, v70, v71
	v_cvt_pk_bf16_f32 v66, v66, v67
	v_cvt_pk_bf16_f32 v67, v74, v75
	v_lshl_add_u64 v[68:69], v[68:69], 0, v[114:115]
	global_store_dwordx4 v[68:69], v[64:67], off nt
	s_nop 1
	v_mul_f32_e32 v64, 0xbfb8aa3b, v60
	v_mul_f32_e32 v65, 0xbfb8aa3b, v61
	v_mul_f32_e32 v66, 0xbfb8aa3b, v62
	v_mul_f32_e32 v67, 0xbfb8aa3b, v63
	v_exp_f32_e32 v64, v64
	v_exp_f32_e32 v65, v65
	v_exp_f32_e32 v66, v66
	v_exp_f32_e32 v67, v67
	v_add_f32_e32 v64, 1.0, v64
	v_add_f32_e32 v65, 1.0, v65
	v_add_f32_e32 v66, 1.0, v66
	v_add_f32_e32 v67, 1.0, v67
	v_rcp_f32_e32 v64, v64
	v_rcp_f32_e32 v65, v65
	v_rcp_f32_e32 v66, v66
	v_rcp_f32_e32 v67, v67
	v_pk_mul_f32 v[60:61], v[60:61], v[64:65]
	s_nop 0
	v_pk_mul_f32 v[52:53], v[52:53], v[60:61]
	v_pk_mul_f32 v[62:63], v[62:63], v[66:67]
	v_mul_f32_e32 v60, 0xbfb8aa3b, v56
	v_pk_mul_f32 v[54:55], v[54:55], v[62:63]
	v_mul_f32_e32 v61, 0xbfb8aa3b, v57
	v_mul_f32_e32 v62, 0xbfb8aa3b, v58
	v_mul_f32_e32 v63, 0xbfb8aa3b, v59
	v_exp_f32_e32 v60, v60
	v_exp_f32_e32 v61, v61
	v_exp_f32_e32 v62, v62
	v_exp_f32_e32 v63, v63
	v_add_f32_e32 v60, 1.0, v60
	v_add_f32_e32 v61, 1.0, v61
	v_add_f32_e32 v62, 1.0, v62
	v_add_f32_e32 v63, 1.0, v63
	v_rcp_f32_e32 v60, v60
	v_rcp_f32_e32 v61, v61
	v_rcp_f32_e32 v62, v62
	v_rcp_f32_e32 v63, v63
	v_pk_mul_f32 v[56:57], v[56:57], v[60:61]
	v_pk_mul_f32 v[58:59], v[58:59], v[62:63]
	s_nop 0
	v_pk_mul_f32 v[58:59], v[50:51], v[58:59]
	v_pk_mul_f32 v[50:51], v[48:49], v[56:57]
	v_cvt_pk_bf16_f32 v48, v52, v53
	v_mad_i64_i32 v[52:53], s[14:15], v152, s68, v[112:113]
	v_cvt_pk_bf16_f32 v49, v54, v55
	v_cvt_pk_bf16_f32 v50, v50, v51
	v_cvt_pk_bf16_f32 v51, v58, v59
	v_lshl_add_u64 v[52:53], v[52:53], 0, v[114:115]
	global_store_dwordx4 v[52:53], v[48:51], off nt
	s_nop 1
	v_mul_f32_e32 v48, 0xbfb8aa3b, v44
	v_mul_f32_e32 v49, 0xbfb8aa3b, v45
	v_mul_f32_e32 v50, 0xbfb8aa3b, v46
	v_mul_f32_e32 v51, 0xbfb8aa3b, v47
	v_exp_f32_e32 v48, v48
	v_exp_f32_e32 v49, v49
	v_exp_f32_e32 v50, v50
	v_exp_f32_e32 v51, v51
	v_add_f32_e32 v48, 1.0, v48
	v_add_f32_e32 v49, 1.0, v49
	v_add_f32_e32 v50, 1.0, v50
	v_add_f32_e32 v51, 1.0, v51
	v_rcp_f32_e32 v48, v48
	v_rcp_f32_e32 v49, v49
	v_rcp_f32_e32 v50, v50
	v_rcp_f32_e32 v51, v51
	v_pk_mul_f32 v[44:45], v[44:45], v[48:49]
	s_nop 0
	v_pk_mul_f32 v[36:37], v[36:37], v[44:45]
	v_pk_mul_f32 v[46:47], v[46:47], v[50:51]
	v_mul_f32_e32 v44, 0xbfb8aa3b, v40
	v_pk_mul_f32 v[38:39], v[38:39], v[46:47]
	v_mul_f32_e32 v45, 0xbfb8aa3b, v41
	v_mul_f32_e32 v46, 0xbfb8aa3b, v42
	v_mul_f32_e32 v47, 0xbfb8aa3b, v43
	v_exp_f32_e32 v44, v44
	v_exp_f32_e32 v45, v45
	v_exp_f32_e32 v46, v46
; __device__ __forceinline__ f32x4 silu4(f32x4 v) { return (f32x4){silu_f(v[0]), silu_f(v[1]), silu_f(v[2]), silu_f(v[3])}; }
; __device__ __forceinline__ u32x4 pack8(f32x4 a, f32x4 b) { u32x4 w; w.x = cvt_pk_bf16(a[0], a[1]); w.y = cvt_pk_bf16(a[2], a[3]); w.z = cvt_pk_bf16(b[0], b[1]); w.w = cvt_pk_bf16(b[2], b[3]); return w; }
;     __device__ __forceinline__ void operator()(const f32x4 (&acc)[2][2][4][2], const Unit& u, int wr, int wc, int fr, int fq) const {
;     ...
;         for (int ai = 0; ai < 2; ++ai)
; #pragma unroll
;             for (int m = 0; m < 4; ++m) {
;                 const int row = u.pm * BM + ai * HALF + wr * 64 + m * 16 + fr;
;                 const float rstd = rs[ai][m];
;                 const f32x4 a0 = silu4(acc[ai][0][m][0] * rstd) * (acc[ai][1][m][0] * rstd);
;                 const f32x4 a1 = silu4(acc[ai][0][m][1] * rstd) * (acc[ai][1][m][1] * rstd);
;                 *(u32x4*)(ACT + (size_t)row * 2816 + col0) = pack8(a0, a1);
;             }
	v_exp_f32_e32 v47, v47
	v_add_f32_e32 v44, 1.0, v44
	v_add_f32_e32 v45, 1.0, v45
	v_add_f32_e32 v46, 1.0, v46
	v_add_f32_e32 v47, 1.0, v47
	v_rcp_f32_e32 v44, v44
	v_rcp_f32_e32 v45, v45
	v_rcp_f32_e32 v46, v46
	v_rcp_f32_e32 v47, v47
	v_pk_mul_f32 v[40:41], v[40:41], v[44:45]
	v_pk_mul_f32 v[42:43], v[42:43], v[46:47]
	s_nop 0
	v_pk_mul_f32 v[42:43], v[34:35], v[42:43]
	v_pk_mul_f32 v[34:35], v[32:33], v[40:41]
	v_cvt_pk_bf16_f32 v32, v36, v37
	v_mad_i64_i32 v[36:37], s[14:15], v150, s68, v[112:113]
	v_cvt_pk_bf16_f32 v33, v38, v39
	v_cvt_pk_bf16_f32 v34, v34, v35
	v_cvt_pk_bf16_f32 v35, v42, v43
	v_lshl_add_u64 v[36:37], v[36:37], 0, v[114:115]
	global_store_dwordx4 v[36:37], v[32:35], off nt
	s_nop 1
	v_mul_f32_e32 v32, 0xbfb8aa3b, v28
	v_mul_f32_e32 v33, 0xbfb8aa3b, v29
	v_mul_f32_e32 v34, 0xbfb8aa3b, v30
	v_mul_f32_e32 v35, 0xbfb8aa3b, v31
	v_exp_f32_e32 v32, v32
	v_exp_f32_e32 v33, v33
	v_exp_f32_e32 v34, v34
	v_exp_f32_e32 v35, v35
	v_add_f32_e32 v32, 1.0, v32
	v_add_f32_e32 v33, 1.0, v33
	v_add_f32_e32 v34, 1.0, v34
	v_add_f32_e32 v35, 1.0, v35
	v_rcp_f32_e32 v32, v32
	v_rcp_f32_e32 v33, v33
	v_rcp_f32_e32 v34, v34
	v_rcp_f32_e32 v35, v35
	v_pk_mul_f32 v[28:29], v[28:29], v[32:33]
	s_nop 0
	v_pk_mul_f32 v[20:21], v[20:21], v[28:29]
	v_pk_mul_f32 v[30:31], v[30:31], v[34:35]
	v_mul_f32_e32 v28, 0xbfb8aa3b, v24
	v_pk_mul_f32 v[22:23], v[22:23], v[30:31]
	v_mul_f32_e32 v29, 0xbfb8aa3b, v25
	v_mul_f32_e32 v30, 0xbfb8aa3b, v26
	v_mul_f32_e32 v31, 0xbfb8aa3b, v27
	v_exp_f32_e32 v28, v28
	v_exp_f32_e32 v29, v29
	v_exp_f32_e32 v30, v30
	v_exp_f32_e32 v31, v31
	v_add_f32_e32 v28, 1.0, v28
	v_add_f32_e32 v29, 1.0, v29
	v_add_f32_e32 v30, 1.0, v30
	v_add_f32_e32 v31, 1.0, v31
	v_rcp_f32_e32 v28, v28
	v_rcp_f32_e32 v29, v29
	v_rcp_f32_e32 v30, v30
	v_rcp_f32_e32 v31, v31
	v_pk_mul_f32 v[24:25], v[24:25], v[28:29]
	v_pk_mul_f32 v[26:27], v[26:27], v[30:31]
	s_nop 0
	v_pk_mul_f32 v[26:27], v[18:19], v[26:27]
	v_pk_mul_f32 v[18:19], v[16:17], v[24:25]
	v_cvt_pk_bf16_f32 v16, v20, v21
	v_mad_i64_i32 v[20:21], s[14:15], v148, s68, v[112:113]
	v_cvt_pk_bf16_f32 v17, v22, v23
	v_cvt_pk_bf16_f32 v18, v18, v19
	v_cvt_pk_bf16_f32 v19, v26, v27
	v_lshl_add_u64 v[20:21], v[20:21], 0, v[114:115]
	global_store_dwordx4 v[20:21], v[16:19], off nt
	s_nop 1
	v_mul_f32_e32 v16, 0xbfb8aa3b, v12
	v_mul_f32_e32 v17, 0xbfb8aa3b, v13
	v_mul_f32_e32 v18, 0xbfb8aa3b, v14
	v_mul_f32_e32 v19, 0xbfb8aa3b, v15
	v_exp_f32_e32 v16, v16
	v_exp_f32_e32 v17, v17
	v_exp_f32_e32 v18, v18
	v_exp_f32_e32 v19, v19
	v_add_f32_e32 v16, 1.0, v16
	v_add_f32_e32 v17, 1.0, v17
	v_add_f32_e32 v18, 1.0, v18
	v_add_f32_e32 v19, 1.0, v19
	v_rcp_f32_e32 v16, v16
	v_rcp_f32_e32 v17, v17
	v_rcp_f32_e32 v18, v18
	v_rcp_f32_e32 v19, v19
	v_pk_mul_f32 v[12:13], v[12:13], v[16:17]
	s_nop 0
	v_pk_mul_f32 v[4:5], v[4:5], v[12:13]
	v_pk_mul_f32 v[14:15], v[14:15], v[18:19]
	v_mul_f32_e32 v12, 0xbfb8aa3b, v8
	v_pk_mul_f32 v[6:7], v[6:7], v[14:15]
	v_mul_f32_e32 v13, 0xbfb8aa3b, v9
	v_mul_f32_e32 v14, 0xbfb8aa3b, v10
	v_mul_f32_e32 v15, 0xbfb8aa3b, v11
	v_exp_f32_e32 v12, v12
	v_exp_f32_e32 v13, v13
	v_exp_f32_e32 v14, v14
	v_exp_f32_e32 v15, v15
	v_add_f32_e32 v12, 1.0, v12
	v_add_f32_e32 v13, 1.0, v13
	v_add_f32_e32 v14, 1.0, v14
	v_add_f32_e32 v15, 1.0, v15
	v_rcp_f32_e32 v12, v12
	v_rcp_f32_e32 v13, v13
	v_rcp_f32_e32 v14, v14
	v_rcp_f32_e32 v15, v15
	v_pk_mul_f32 v[8:9], v[8:9], v[12:13]
	v_pk_mul_f32 v[10:11], v[10:11], v[14:15]
	s_nop 0
	v_pk_mul_f32 v[10:11], v[2:3], v[10:11]
	v_pk_mul_f32 v[2:3], v[0:1], v[8:9]
	v_cvt_pk_bf16_f32 v0, v4, v5
	v_mad_i64_i32 v[4:5], s[14:15], v146, s68, v[112:113]
	v_lshl_add_u64 v[4:5], v[4:5], 0, v[114:115]
	v_cvt_pk_bf16_f32 v1, v6, v7
	v_cvt_pk_bf16_f32 v2, v2, v3
	v_cvt_pk_bf16_f32 v3, v10, v11
	global_store_dwordx4 v[4:5], v[0:3], off nt
	s_cbranch_vccnz .LBB0_992
	s_andn2_b64 vcc, exec, s[18:19]
	s_cbranch_vccnz .LBB0_991
	s_barrier
	s_branch .LBB0_991

; __device__ __forceinline__ float row_part(const float* ss, int row, int fq) { const f32x4 a = ((const f32x4*)(ss + (size_t)row * 16))[fq]; return (a[0] + a[1]) + (a[2] + a[3]); }
; __device__ __forceinline__ float row_finish(float t) { t += shx(t, 16); t += shx(t, 32); return __builtin_amdgcn_rsqf(t * (1.0f / 1024.0f) + RMS_EPS); }
;     __device__ __forceinline__ void operator()(const f32x4 (&acc)[2][2][4][2], const Unit& u, int wr, int wc, int fr, int fq) const {
;         const int col0 = u.pn * 128 + 32 * wc + 8 * fq;
;         float rs[2][4];
; #pragma unroll
;         for (int ai = 0; ai < 2; ++ai)
; #pragma unroll
;             for (int m = 0; m < 4; ++m) rs[ai][m] = row_part(ss, u.pm * BM + ai * HALF + wr * 64 + m * 16 + fr, fq);
; #pragma unroll
;         for (int ai = 0; ai < 2; ++ai)
; #pragma unroll
;             for (int m = 0; m < 4; ++m) rs[ai][m] = row_finish(rs[ai][m]);
.LBB0_1591:
	v_lshl_add_u32 v170, s44, 8, v153
	v_ashrrev_i32_e32 v171, 31, v170
	v_or_b32_e32 v166, 16, v170
	v_lshlrev_b64 v[146:147], 6, v[170:171]
	v_ashrrev_i32_e32 v167, 31, v166
	v_lshl_add_u64 v[146:147], v[136:137], 0, v[146:147]
	v_lshlrev_b64 v[148:149], 6, v[166:167]
	v_lshl_add_u64 v[148:149], v[136:137], 0, v[148:149]
	ds_read_b128 v[176:179], v239
	ds_read_b128 v[180:183], v239 offset:1024
	v_or_b32_e32 v162, 32, v170
	v_ashrrev_i32_e32 v163, 31, v162
	v_or_b32_e32 v158, 48, v170
	v_lshlrev_b64 v[146:147], 6, v[162:163]
	v_ashrrev_i32_e32 v159, 31, v158
	v_lshl_add_u64 v[146:147], v[136:137], 0, v[146:147]
	v_lshlrev_b64 v[148:149], 6, v[158:159]
	v_lshl_add_u64 v[148:149], v[136:137], 0, v[148:149]
	ds_read_b128 v[184:187], v239 offset:2048
	ds_read_b128 v[188:191], v239 offset:3072
	v_add_u32_e32 v154, 0x80, v170
	v_ashrrev_i32_e32 v155, 31, v154
	v_add_u32_e32 v150, 0x90, v170
	v_lshlrev_b64 v[146:147], 6, v[154:155]
	v_ashrrev_i32_e32 v151, 31, v150
	v_lshl_add_u64 v[146:147], v[136:137], 0, v[146:147]
	v_lshlrev_b64 v[148:149], 6, v[150:151]
	v_lshl_add_u64 v[148:149], v[136:137], 0, v[148:149]
	ds_read_b128 v[192:195], v239 offset:8192
	ds_read_b128 v[196:199], v239 offset:9216
	v_add_u32_e32 v148, 0xa0, v170
	v_ashrrev_i32_e32 v149, 31, v148
	v_lshlrev_b64 v[146:147], 6, v[148:149]
	v_lshl_add_u64 v[146:147], v[136:137], 0, v[146:147]
	ds_read_b128 v[202:205], v239 offset:10240
	v_add_u32_e32 v146, 0xb0, v170
	v_ashrrev_i32_e32 v147, 31, v146
	v_lshlrev_b64 v[206:207], 6, v[146:147]
	v_lshl_add_u64 v[206:207], v[136:137], 0, v[206:207]
	ds_read_b128 v[206:209], v239 offset:11264
	v_mov_b32_e32 v147, v201
	v_mov_b32_e32 v149, v201
	v_lshlrev_b32_e32 v147, 2, v147
	v_mov_b32_e32 v151, v201
	v_xor_b32_e32 v147, 64, v147
	s_andn2_b64 vcc, exec, s[8:9]
	v_lshlrev_b32_e32 v151, 2, v151
	v_xor_b32_e32 v151, 64, v151
	v_lshlrev_b32_e32 v149, 2, v149
	v_xor_b32_e32 v149, 0x80, v149
	s_mov_b64 s[8:9], -1
	s_waitcnt lgkmcnt(0)
	v_mov_b32_e32 v210, v177
	v_mov_b32_e32 v211, v178
	v_mov_b32_e32 v177, v179
	v_pk_add_f32 v[176:177], v[210:211], v[176:177]
	v_mov_b32_e32 v178, v181
	v_add_f32_e32 v152, v176, v177
	v_mov_b32_e32 v179, v182
	v_mov_b32_e32 v181, v183
	v_mov_b32_e32 v147, v152
	s_nop 1
	v_permlane16_swap_b32_e32 v147, v152
	v_pk_add_f32 v[176:177], v[178:179], v[180:181]
	v_mov_b32_e32 v182, v185
	v_add_f32_e32 v155, v176, v177
	v_mov_b32_e32 v151, v155
	s_nop 1
	v_permlane16_swap_b32_e32 v151, v155
	s_waitcnt lgkmcnt(0)
	v_add_f32_e32 v147, v152, v147
	v_mov_b32_e32 v152, v201
	v_mov_b32_e32 v149, v147
	s_nop 1
	v_permlane32_swap_b32_e32 v149, v147
	s_waitcnt lgkmcnt(0)
	v_add_f32_e32 v151, v155, v151
	v_lshlrev_b32_e32 v152, 2, v152
	v_xor_b32_e32 v152, 0x80, v152
	v_mov_b32_e32 v152, v151
	s_nop 1
	v_permlane32_swap_b32_e32 v152, v151
	s_waitcnt lgkmcnt(0)
	v_add_f32_e32 v147, v147, v149
	v_mov_b32_e32 v149, v201
	v_mov_b32_e32 v183, v186
	v_mov_b32_e32 v185, v187
	v_pk_add_f32 v[178:179], v[182:183], v[184:185]
	v_fmamk_f32 v147, v147, 0x3a800000, v175
	v_lshlrev_b32_e32 v149, 2, v149
	v_add_f32_e32 v156, v178, v179
	v_rsq_f32_e32 v176, v147
	s_waitcnt lgkmcnt(0)
	v_add_f32_e32 v147, v151, v152
	v_xor_b32_e32 v149, 64, v149
	v_mov_b32_e32 v151, v201
	v_mov_b32_e32 v152, v201
	v_mov_b32_e32 v186, v189
	v_mov_b32_e32 v187, v190
	v_mov_b32_e32 v189, v191
	v_mov_b32_e32 v149, v156
	s_nop 1
	v_permlane16_swap_b32_e32 v149, v156
	v_pk_add_f32 v[180:181], v[186:187], v[188:189]
	v_lshlrev_b32_e32 v152, 2, v152
	v_add_f32_e32 v159, v180, v181
	v_xor_b32_e32 v152, 64, v152
	v_mov_b32_e32 v152, v159
	s_nop 1
	v_permlane16_swap_b32_e32 v152, v159
	s_waitcnt lgkmcnt(0)
	v_add_f32_e32 v149, v156, v149
	v_lshlrev_b32_e32 v151, 2, v151
	v_mov_b32_e32 v156, v201
	v_xor_b32_e32 v151, 0x80, v151
	v_mov_b32_e32 v151, v149
	s_nop 1
	v_permlane32_swap_b32_e32 v151, v149
	v_lshlrev_b32_e32 v156, 2, v156
	s_waitcnt lgkmcnt(0)
	v_add_f32_e32 v152, v159, v152
	v_xor_b32_e32 v156, 0x80, v156
	v_mov_b32_e32 v156, v152
	s_nop 1
	v_permlane32_swap_b32_e32 v156, v152
	v_fmamk_f32 v147, v147, 0x3a800000, v175
	v_rsq_f32_e32 v174, v147
	s_waitcnt lgkmcnt(0)
	v_add_f32_e32 v147, v149, v151
	v_mov_b32_e32 v149, v201
	v_mov_b32_e32 v190, v193
	v_mov_b32_e32 v191, v194
	v_mov_b32_e32 v193, v195
	v_fmamk_f32 v147, v147, 0x3a800000, v175
	v_pk_add_f32 v[182:183], v[190:191], v[192:193]
	v_rsq_f32_e32 v172, v147
	s_waitcnt lgkmcnt(0)
	v_add_f32_e32 v147, v152, v156
	v_lshlrev_b32_e32 v149, 2, v149
	v_mov_b32_e32 v151, v201
	v_mov_b32_e32 v152, v201
	v_mov_b32_e32 v194, v197
	v_mov_b32_e32 v195, v198
	v_mov_b32_e32 v197, v199
	v_add_f32_e32 v160, v182, v183
	v_xor_b32_e32 v149, 64, v149
	v_pk_add_f32 v[184:185], v[194:195], v[196:197]
	v_mov_b32_e32 v149, v160
	s_nop 1
	v_permlane16_swap_b32_e32 v149, v160
	v_lshlrev_b32_e32 v152, 2, v152
	v_add_f32_e32 v163, v184, v185
	v_xor_b32_e32 v152, 64, v152
	v_mov_b32_e32 v152, v163
	s_nop 1
	v_permlane16_swap_b32_e32 v152, v163
	v_lshlrev_b32_e32 v151, 2, v151
	v_mov_b32_e32 v156, v201
	s_waitcnt lgkmcnt(0)
	v_add_f32_e32 v149, v160, v149
	v_xor_b32_e32 v151, 0x80, v151
	v_mov_b32_e32 v151, v149
	s_nop 1
	v_permlane32_swap_b32_e32 v151, v149
	v_lshlrev_b32_e32 v156, 2, v156
	s_waitcnt lgkmcnt(0)
	v_add_f32_e32 v152, v163, v152
	v_xor_b32_e32 v156, 0x80, v156
	v_mov_b32_e32 v156, v152
	s_nop 1
	v_permlane32_swap_b32_e32 v156, v152
	v_fmamk_f32 v147, v147, 0x3a800000, v175
	v_rsq_f32_e32 v168, v147
	s_waitcnt lgkmcnt(0)
	v_add_f32_e32 v147, v149, v151
	v_fmamk_f32 v147, v147, 0x3a800000, v175
	v_rsq_f32_e32 v164, v147
	s_waitcnt lgkmcnt(0)
; __device__ __forceinline__ float row_finish(float t) { t += shx(t, 16); t += shx(t, 32); return __builtin_amdgcn_rsqf(t * (1.0f / 1024.0f) + RMS_EPS); }
; __device__ __forceinline__ f32x4 silu4(f32x4 v) { return (f32x4){silu_f(v[0]), silu_f(v[1]), silu_f(v[2]), silu_f(v[3])}; }
; __device__ __forceinline__ u32x4 pack8(f32x4 a, f32x4 b) { u32x4 w; w.x = cvt_pk_bf16(a[0], a[1]); w.y = cvt_pk_bf16(a[2], a[3]); w.z = cvt_pk_bf16(b[0], b[1]); w.w = cvt_pk_bf16(b[2], b[3]); return w; }
;     __device__ __forceinline__ void operator()(const f32x4 (&acc)[2][2][4][2], const Unit& u, int wr, int wc, int fr, int fq) const {
;     ...
;             for (int m = 0; m < 4; ++m) rs[ai][m] = row_finish(rs[ai][m]);
; #pragma unroll
;         for (int ai = 0; ai < 2; ++ai)
; #pragma unroll
;             for (int m = 0; m < 4; ++m) {
;                 const int row = u.pm * BM + ai * HALF + wr * 64 + m * 16 + fr;
;                 const float rstd = rs[ai][m];
;                 const f32x4 a0 = silu4(acc[ai][0][m][0] * rstd) * (acc[ai][1][m][0] * rstd);
;                 const f32x4 a1 = silu4(acc[ai][0][m][1] * rstd) * (acc[ai][1][m][1] * rstd);
;                 *(u32x4*)(ACT + (size_t)row * 2816 + col0) = pack8(a0, a1);
	v_add_f32_e32 v147, v152, v156
	v_mov_b32_e32 v149, v201
	v_mov_b32_e32 v151, v201
	v_mov_b32_e32 v152, v201
	v_mov_b32_e32 v198, v203
	v_mov_b32_e32 v199, v204
	v_mov_b32_e32 v203, v205
	v_mov_b32_e32 v204, v207
	v_mov_b32_e32 v205, v208
	v_mov_b32_e32 v207, v209
	v_pk_add_f32 v[188:189], v[204:205], v[206:207]
	v_lshlrev_b32_e32 v152, 2, v152
	v_pk_add_f32 v[186:187], v[198:199], v[202:203]
	v_add_f32_e32 v155, v188, v189
	v_lshlrev_b32_e32 v149, 2, v149
	v_xor_b32_e32 v152, 64, v152
	v_add_f32_e32 v167, v186, v187
	v_xor_b32_e32 v149, 64, v149
	v_mov_b32_e32 v152, v155
	s_nop 1
	v_permlane16_swap_b32_e32 v152, v155
	v_mov_b32_e32 v149, v167
	s_nop 1
	v_permlane16_swap_b32_e32 v149, v167
	v_lshlrev_b32_e32 v151, 2, v151
	v_xor_b32_e32 v151, 0x80, v151
	v_fmamk_f32 v147, v147, 0x3a800000, v175
	s_waitcnt lgkmcnt(0)
	v_add_f32_e32 v152, v155, v152
	v_mov_b32_e32 v155, v201
	s_waitcnt lgkmcnt(0)
	v_add_f32_e32 v149, v167, v149
	v_mov_b32_e32 v151, v149
	s_nop 1
	v_permlane32_swap_b32_e32 v151, v149
	v_lshlrev_b32_e32 v155, 2, v155
	v_xor_b32_e32 v155, 0x80, v155
	v_mov_b32_e32 v155, v152
	s_nop 1
	v_permlane32_swap_b32_e32 v155, v152
	v_rsq_f32_e32 v160, v147
	s_waitcnt lgkmcnt(0)
	v_add_f32_e32 v147, v149, v151
	v_fmamk_f32 v147, v147, 0x3a800000, v175
	v_rsq_f32_e32 v156, v147
	s_waitcnt lgkmcnt(0)
	v_add_f32_e32 v147, v152, v155
	v_fmamk_f32 v147, v147, 0x3a800000, v175
	v_pk_mul_f32 v[124:125], v[124:125], v[176:177] op_sel_hi:[1,0]
	v_rsq_f32_e32 v152, v147
	v_mul_f32_e32 v147, 0xbfb8aa3b, v124
	v_exp_f32_e32 v147, v147
	v_mul_f32_e32 v149, 0xbfb8aa3b, v125
	v_exp_f32_e32 v149, v149
	v_pk_mul_f32 v[126:127], v[126:127], v[176:177] op_sel_hi:[1,0]
	v_add_f32_e32 v147, 1.0, v147
	v_rcp_f32_e32 v178, v147
	v_add_f32_e32 v147, 1.0, v149
	v_mul_f32_e32 v149, 0xbfb8aa3b, v126
	v_exp_f32_e32 v149, v149
	v_mul_f32_e32 v151, 0xbfb8aa3b, v127
	v_exp_f32_e32 v151, v151
	v_rcp_f32_e32 v179, v147
	v_add_f32_e32 v147, 1.0, v149
	v_rcp_f32_e32 v180, v147
	v_add_f32_e32 v147, 1.0, v151
	v_pk_mul_f32 v[120:121], v[120:121], v[176:177] op_sel_hi:[1,0]
	v_rcp_f32_e32 v181, v147
	v_mul_f32_e32 v147, 0xbfb8aa3b, v120
	v_exp_f32_e32 v147, v147
	v_mul_f32_e32 v149, 0xbfb8aa3b, v121
	v_exp_f32_e32 v149, v149
	v_pk_mul_f32 v[122:123], v[122:123], v[176:177] op_sel_hi:[1,0]
	v_add_f32_e32 v147, 1.0, v147
	v_pk_mul_f32 v[124:125], v[124:125], v[178:179]
	v_rcp_f32_e32 v178, v147
	v_add_f32_e32 v147, 1.0, v149
	v_mul_f32_e32 v149, 0xbfb8aa3b, v122
	v_exp_f32_e32 v149, v149
	v_mul_f32_e32 v151, 0xbfb8aa3b, v123
	v_exp_f32_e32 v151, v151
	v_rcp_f32_e32 v179, v147
	v_add_f32_e32 v147, 1.0, v149
	v_pk_mul_f32 v[126:127], v[126:127], v[180:181]
	v_rcp_f32_e32 v180, v147
	v_add_f32_e32 v147, 1.0, v151
	v_rcp_f32_e32 v181, v147
	v_pk_mul_f32 v[116:117], v[116:117], v[176:177] op_sel_hi:[1,0]
	v_pk_mul_f32 v[118:119], v[118:119], v[176:177] op_sel_hi:[1,0]
	v_pk_mul_f32 v[120:121], v[120:121], v[178:179]
	v_pk_mul_f32 v[112:113], v[112:113], v[176:177] op_sel_hi:[1,0]
	v_lshl_or_b32 v182, s61, 7, v161
	v_pk_mul_f32 v[118:119], v[118:119], v[126:127]
	v_pk_mul_f32 v[116:117], v[116:117], v[124:125]
	v_pk_mul_f32 v[122:123], v[122:123], v[180:181]
	v_pk_mul_f32 v[114:115], v[114:115], v[176:177] op_sel_hi:[1,0]
	v_pk_mul_f32 v[112:113], v[112:113], v[120:121]
	v_ashrrev_i32_e32 v183, 31, v182
	v_pk_mul_f32 v[114:115], v[114:115], v[122:123]
	v_cvt_pk_bf16_f32 v116, v116, v117
	v_cvt_pk_bf16_f32 v117, v118, v119
	v_cvt_pk_bf16_f32 v118, v112, v113
	v_mov_b64_e32 v[112:113], s[16:17]
	v_cvt_pk_bf16_f32 v119, v114, v115
	v_mad_i64_i32 v[120:121], s[46:47], v170, s60, v[112:113]
	v_lshlrev_b64 v[114:115], 1, v[182:183]
	v_pk_mul_f32 v[108:109], v[108:109], v[174:175] op_sel_hi:[1,0]
	v_pk_mul_f32 v[110:111], v[110:111], v[174:175] op_sel_hi:[1,0]
	v_mul_f32_e32 v122, 0xbfb8aa3b, v108
	v_mul_f32_e32 v123, 0xbfb8aa3b, v109
	v_lshl_add_u64 v[120:121], v[120:121], 0, v[114:115]
	v_pk_mul_f32 v[104:105], v[104:105], v[174:175] op_sel_hi:[1,0]
	v_pk_mul_f32 v[106:107], v[106:107], v[174:175] op_sel_hi:[1,0]
	v_exp_f32_e32 v122, v122
	v_exp_f32_e32 v123, v123
	v_mul_f32_e32 v124, 0xbfb8aa3b, v110
	v_mul_f32_e32 v125, 0xbfb8aa3b, v111
	global_store_dwordx4 v[120:121], v[116:119], off nt
	v_exp_f32_e32 v124, v124
	v_exp_f32_e32 v125, v125
	v_mul_f32_e32 v116, 0xbfb8aa3b, v104
	v_mul_f32_e32 v117, 0xbfb8aa3b, v105
	v_mul_f32_e32 v118, 0xbfb8aa3b, v106
	v_mul_f32_e32 v119, 0xbfb8aa3b, v107
	v_exp_f32_e32 v116, v116
	v_exp_f32_e32 v117, v117
	v_exp_f32_e32 v118, v118
	v_exp_f32_e32 v119, v119
	v_add_f32_e32 v122, 1.0, v122
	v_add_f32_e32 v123, 1.0, v123
	v_rcp_f32_e32 v122, v122
	v_rcp_f32_e32 v123, v123
	v_add_f32_e32 v124, 1.0, v124
	v_add_f32_e32 v125, 1.0, v125
	v_add_f32_e32 v116, 1.0, v116
	v_add_f32_e32 v117, 1.0, v117
	v_add_f32_e32 v118, 1.0, v118
	v_add_f32_e32 v119, 1.0, v119
	v_rcp_f32_e32 v124, v124
	v_rcp_f32_e32 v125, v125
	v_rcp_f32_e32 v116, v116
	v_rcp_f32_e32 v117, v117
	v_rcp_f32_e32 v118, v118
	v_rcp_f32_e32 v119, v119
	v_pk_mul_f32 v[108:109], v[108:109], v[122:123]
	v_pk_mul_f32 v[100:101], v[100:101], v[174:175] op_sel_hi:[1,0]
	v_pk_mul_f32 v[110:111], v[110:111], v[124:125]
	v_pk_mul_f32 v[102:103], v[102:103], v[174:175] op_sel_hi:[1,0]
	v_pk_mul_f32 v[100:101], v[100:101], v[108:109]
	v_pk_mul_f32 v[104:105], v[104:105], v[116:117]
	v_pk_mul_f32 v[106:107], v[106:107], v[118:119]
	v_pk_mul_f32 v[96:97], v[96:97], v[174:175] op_sel_hi:[1,0]
	v_pk_mul_f32 v[98:99], v[98:99], v[174:175] op_sel_hi:[1,0]
	v_pk_mul_f32 v[102:103], v[102:103], v[110:111]
	v_pk_mul_f32 v[106:107], v[98:99], v[106:107]
	v_pk_mul_f32 v[98:99], v[96:97], v[104:105]
; __device__ __forceinline__ f32x4 silu4(f32x4 v) { return (f32x4){silu_f(v[0]), silu_f(v[1]), silu_f(v[2]), silu_f(v[3])}; }
; __device__ __forceinline__ u32x4 pack8(f32x4 a, f32x4 b) { u32x4 w; w.x = cvt_pk_bf16(a[0], a[1]); w.y = cvt_pk_bf16(a[2], a[3]); w.z = cvt_pk_bf16(b[0], b[1]); w.w = cvt_pk_bf16(b[2], b[3]); return w; }
;     __device__ __forceinline__ void operator()(const f32x4 (&acc)[2][2][4][2], const Unit& u, int wr, int wc, int fr, int fq) const {
;     ...
;         for (int ai = 0; ai < 2; ++ai)
; #pragma unroll
;             for (int m = 0; m < 4; ++m) {
;                 const int row = u.pm * BM + ai * HALF + wr * 64 + m * 16 + fr;
;                 const float rstd = rs[ai][m];
;                 const f32x4 a0 = silu4(acc[ai][0][m][0] * rstd) * (acc[ai][1][m][0] * rstd);
;                 const f32x4 a1 = silu4(acc[ai][0][m][1] * rstd) * (acc[ai][1][m][1] * rstd);
;                 *(u32x4*)(ACT + (size_t)row * 2816 + col0) = pack8(a0, a1);
;             }
	v_cvt_pk_bf16_f32 v96, v100, v101
	v_mad_i64_i32 v[100:101], s[46:47], v166, s60, v[112:113]
	v_pk_mul_f32 v[92:93], v[92:93], v[172:173] op_sel_hi:[1,0]
	v_cvt_pk_bf16_f32 v97, v102, v103
	v_cvt_pk_bf16_f32 v98, v98, v99
	v_cvt_pk_bf16_f32 v99, v106, v107
	v_pk_mul_f32 v[94:95], v[94:95], v[172:173] op_sel_hi:[1,0]
	v_mul_f32_e32 v102, 0xbfb8aa3b, v92
	v_mul_f32_e32 v103, 0xbfb8aa3b, v93
	v_lshl_add_u64 v[100:101], v[100:101], 0, v[114:115]
	v_pk_mul_f32 v[88:89], v[88:89], v[172:173] op_sel_hi:[1,0]
	v_pk_mul_f32 v[90:91], v[90:91], v[172:173] op_sel_hi:[1,0]
	v_exp_f32_e32 v102, v102
	v_exp_f32_e32 v103, v103
	v_mul_f32_e32 v104, 0xbfb8aa3b, v94
	v_mul_f32_e32 v105, 0xbfb8aa3b, v95
	global_store_dwordx4 v[100:101], v[96:99], off nt
	v_exp_f32_e32 v104, v104
	v_exp_f32_e32 v105, v105
	v_mul_f32_e32 v96, 0xbfb8aa3b, v88
	v_mul_f32_e32 v97, 0xbfb8aa3b, v89
	v_mul_f32_e32 v98, 0xbfb8aa3b, v90
	v_mul_f32_e32 v99, 0xbfb8aa3b, v91
	v_exp_f32_e32 v96, v96
	v_exp_f32_e32 v97, v97
	v_exp_f32_e32 v98, v98
	v_exp_f32_e32 v99, v99
	v_add_f32_e32 v102, 1.0, v102
	v_add_f32_e32 v103, 1.0, v103
	v_rcp_f32_e32 v102, v102
	v_rcp_f32_e32 v103, v103
	v_add_f32_e32 v104, 1.0, v104
	v_add_f32_e32 v105, 1.0, v105
	v_add_f32_e32 v96, 1.0, v96
	v_add_f32_e32 v97, 1.0, v97
	v_add_f32_e32 v98, 1.0, v98
	v_add_f32_e32 v99, 1.0, v99
	v_rcp_f32_e32 v104, v104
	v_rcp_f32_e32 v105, v105
	v_rcp_f32_e32 v96, v96
	v_rcp_f32_e32 v97, v97
	v_rcp_f32_e32 v98, v98
	v_rcp_f32_e32 v99, v99
	v_pk_mul_f32 v[92:93], v[92:93], v[102:103]
	v_pk_mul_f32 v[84:85], v[84:85], v[172:173] op_sel_hi:[1,0]
	v_pk_mul_f32 v[94:95], v[94:95], v[104:105]
	v_pk_mul_f32 v[86:87], v[86:87], v[172:173] op_sel_hi:[1,0]
	v_pk_mul_f32 v[84:85], v[84:85], v[92:93]
	v_pk_mul_f32 v[88:89], v[88:89], v[96:97]
	v_pk_mul_f32 v[90:91], v[90:91], v[98:99]
	v_pk_mul_f32 v[80:81], v[80:81], v[172:173] op_sel_hi:[1,0]
	v_pk_mul_f32 v[82:83], v[82:83], v[172:173] op_sel_hi:[1,0]
	v_pk_mul_f32 v[86:87], v[86:87], v[94:95]
	v_pk_mul_f32 v[90:91], v[82:83], v[90:91]
	v_pk_mul_f32 v[82:83], v[80:81], v[88:89]
	v_cvt_pk_bf16_f32 v80, v84, v85
	v_mad_i64_i32 v[84:85], s[46:47], v162, s60, v[112:113]
	v_pk_mul_f32 v[76:77], v[76:77], v[168:169] op_sel_hi:[1,0]
	v_cvt_pk_bf16_f32 v81, v86, v87
	v_cvt_pk_bf16_f32 v82, v82, v83
	v_cvt_pk_bf16_f32 v83, v90, v91
	v_pk_mul_f32 v[78:79], v[78:79], v[168:169] op_sel_hi:[1,0]
	v_mul_f32_e32 v86, 0xbfb8aa3b, v76
	v_mul_f32_e32 v87, 0xbfb8aa3b, v77
	v_lshl_add_u64 v[84:85], v[84:85], 0, v[114:115]
	v_pk_mul_f32 v[72:73], v[72:73], v[168:169] op_sel_hi:[1,0]
	v_pk_mul_f32 v[74:75], v[74:75], v[168:169] op_sel_hi:[1,0]
	v_exp_f32_e32 v86, v86
	v_exp_f32_e32 v87, v87
	v_mul_f32_e32 v88, 0xbfb8aa3b, v78
	v_mul_f32_e32 v89, 0xbfb8aa3b, v79
	global_store_dwordx4 v[84:85], v[80:83], off nt
	v_exp_f32_e32 v88, v88
	v_exp_f32_e32 v89, v89
	v_mul_f32_e32 v80, 0xbfb8aa3b, v72
	v_mul_f32_e32 v81, 0xbfb8aa3b, v73
	v_mul_f32_e32 v82, 0xbfb8aa3b, v74
	v_mul_f32_e32 v83, 0xbfb8aa3b, v75
	v_exp_f32_e32 v80, v80
	v_exp_f32_e32 v81, v81
	v_exp_f32_e32 v82, v82
	v_exp_f32_e32 v83, v83
	v_add_f32_e32 v86, 1.0, v86
	v_add_f32_e32 v87, 1.0, v87
	v_rcp_f32_e32 v86, v86
	v_rcp_f32_e32 v87, v87
	v_add_f32_e32 v88, 1.0, v88
	v_add_f32_e32 v89, 1.0, v89
	v_add_f32_e32 v80, 1.0, v80
	v_add_f32_e32 v81, 1.0, v81
	v_add_f32_e32 v82, 1.0, v82
	v_add_f32_e32 v83, 1.0, v83
	v_rcp_f32_e32 v88, v88
	v_rcp_f32_e32 v89, v89
	v_rcp_f32_e32 v80, v80
	v_rcp_f32_e32 v81, v81
	v_rcp_f32_e32 v82, v82
	v_rcp_f32_e32 v83, v83
	v_pk_mul_f32 v[76:77], v[76:77], v[86:87]
	v_pk_mul_f32 v[68:69], v[68:69], v[168:169] op_sel_hi:[1,0]
	v_pk_mul_f32 v[78:79], v[78:79], v[88:89]
	v_pk_mul_f32 v[70:71], v[70:71], v[168:169] op_sel_hi:[1,0]
	v_pk_mul_f32 v[68:69], v[68:69], v[76:77]
	v_pk_mul_f32 v[72:73], v[72:73], v[80:81]
	v_pk_mul_f32 v[74:75], v[74:75], v[82:83]
	v_pk_mul_f32 v[64:65], v[64:65], v[168:169] op_sel_hi:[1,0]
	v_pk_mul_f32 v[66:67], v[66:67], v[168:169] op_sel_hi:[1,0]
	v_pk_mul_f32 v[70:71], v[70:71], v[78:79]
	v_pk_mul_f32 v[74:75], v[66:67], v[74:75]
	v_pk_mul_f32 v[66:67], v[64:65], v[72:73]
	v_cvt_pk_bf16_f32 v64, v68, v69
	v_mad_i64_i32 v[68:69], s[46:47], v158, s60, v[112:113]
	v_pk_mul_f32 v[60:61], v[60:61], v[164:165] op_sel_hi:[1,0]
	v_cvt_pk_bf16_f32 v65, v70, v71
	v_cvt_pk_bf16_f32 v66, v66, v67
	v_cvt_pk_bf16_f32 v67, v74, v75
	v_pk_mul_f32 v[62:63], v[62:63], v[164:165] op_sel_hi:[1,0]
	v_mul_f32_e32 v70, 0xbfb8aa3b, v60
	v_mul_f32_e32 v71, 0xbfb8aa3b, v61
	v_lshl_add_u64 v[68:69], v[68:69], 0, v[114:115]
	v_pk_mul_f32 v[56:57], v[56:57], v[164:165] op_sel_hi:[1,0]
	v_pk_mul_f32 v[58:59], v[58:59], v[164:165] op_sel_hi:[1,0]
	v_exp_f32_e32 v70, v70
	v_exp_f32_e32 v71, v71
	v_mul_f32_e32 v72, 0xbfb8aa3b, v62
	v_mul_f32_e32 v73, 0xbfb8aa3b, v63
	global_store_dwordx4 v[68:69], v[64:67], off nt
	v_exp_f32_e32 v72, v72
	v_exp_f32_e32 v73, v73
	v_mul_f32_e32 v64, 0xbfb8aa3b, v56
	v_mul_f32_e32 v65, 0xbfb8aa3b, v57
	v_mul_f32_e32 v66, 0xbfb8aa3b, v58
	v_mul_f32_e32 v67, 0xbfb8aa3b, v59
	v_exp_f32_e32 v64, v64
	v_exp_f32_e32 v65, v65
	v_exp_f32_e32 v66, v66
	v_exp_f32_e32 v67, v67
	v_add_f32_e32 v70, 1.0, v70
	v_add_f32_e32 v71, 1.0, v71
	v_rcp_f32_e32 v70, v70
	v_rcp_f32_e32 v71, v71
	v_add_f32_e32 v72, 1.0, v72
	v_add_f32_e32 v73, 1.0, v73
	v_add_f32_e32 v64, 1.0, v64
	v_add_f32_e32 v65, 1.0, v65
	v_add_f32_e32 v66, 1.0, v66
	v_add_f32_e32 v67, 1.0, v67
	v_rcp_f32_e32 v72, v72
	v_rcp_f32_e32 v73, v73
	v_rcp_f32_e32 v64, v64
	v_rcp_f32_e32 v65, v65
	v_rcp_f32_e32 v66, v66
	v_rcp_f32_e32 v67, v67
	v_pk_mul_f32 v[60:61], v[60:61], v[70:71]
	v_pk_mul_f32 v[52:53], v[52:53], v[164:165] op_sel_hi:[1,0]
; __device__ __forceinline__ f32x4 silu4(f32x4 v) { return (f32x4){silu_f(v[0]), silu_f(v[1]), silu_f(v[2]), silu_f(v[3])}; }
; __device__ __forceinline__ u32x4 pack8(f32x4 a, f32x4 b) { u32x4 w; w.x = cvt_pk_bf16(a[0], a[1]); w.y = cvt_pk_bf16(a[2], a[3]); w.z = cvt_pk_bf16(b[0], b[1]); w.w = cvt_pk_bf16(b[2], b[3]); return w; }
;     __device__ __forceinline__ void operator()(const f32x4 (&acc)[2][2][4][2], const Unit& u, int wr, int wc, int fr, int fq) const {
;     ...
;         for (int ai = 0; ai < 2; ++ai)
; #pragma unroll
;             for (int m = 0; m < 4; ++m) {
;                 const int row = u.pm * BM + ai * HALF + wr * 64 + m * 16 + fr;
;                 const float rstd = rs[ai][m];
;                 const f32x4 a0 = silu4(acc[ai][0][m][0] * rstd) * (acc[ai][1][m][0] * rstd);
;                 const f32x4 a1 = silu4(acc[ai][0][m][1] * rstd) * (acc[ai][1][m][1] * rstd);
;                 *(u32x4*)(ACT + (size_t)row * 2816 + col0) = pack8(a0, a1);
;             }
	v_pk_mul_f32 v[62:63], v[62:63], v[72:73]
	v_pk_mul_f32 v[54:55], v[54:55], v[164:165] op_sel_hi:[1,0]
	v_pk_mul_f32 v[52:53], v[52:53], v[60:61]
	v_pk_mul_f32 v[56:57], v[56:57], v[64:65]
	v_pk_mul_f32 v[58:59], v[58:59], v[66:67]
	v_pk_mul_f32 v[48:49], v[48:49], v[164:165] op_sel_hi:[1,0]
	v_pk_mul_f32 v[50:51], v[50:51], v[164:165] op_sel_hi:[1,0]
	v_pk_mul_f32 v[54:55], v[54:55], v[62:63]
	v_pk_mul_f32 v[58:59], v[50:51], v[58:59]
	v_pk_mul_f32 v[50:51], v[48:49], v[56:57]
	v_cvt_pk_bf16_f32 v48, v52, v53
	v_mad_i64_i32 v[52:53], s[46:47], v154, s60, v[112:113]
	v_pk_mul_f32 v[44:45], v[44:45], v[160:161] op_sel_hi:[1,0]
	v_cvt_pk_bf16_f32 v49, v54, v55
	v_cvt_pk_bf16_f32 v50, v50, v51
	v_cvt_pk_bf16_f32 v51, v58, v59
	v_pk_mul_f32 v[46:47], v[46:47], v[160:161] op_sel_hi:[1,0]
	v_mul_f32_e32 v54, 0xbfb8aa3b, v44
	v_mul_f32_e32 v55, 0xbfb8aa3b, v45
	v_lshl_add_u64 v[52:53], v[52:53], 0, v[114:115]
	v_pk_mul_f32 v[40:41], v[40:41], v[160:161] op_sel_hi:[1,0]
	v_pk_mul_f32 v[42:43], v[42:43], v[160:161] op_sel_hi:[1,0]
	v_exp_f32_e32 v54, v54
	v_exp_f32_e32 v55, v55
	v_mul_f32_e32 v56, 0xbfb8aa3b, v46
	v_mul_f32_e32 v57, 0xbfb8aa3b, v47
	global_store_dwordx4 v[52:53], v[48:51], off nt
	v_exp_f32_e32 v56, v56
	v_exp_f32_e32 v57, v57
	v_mul_f32_e32 v48, 0xbfb8aa3b, v40
	v_mul_f32_e32 v49, 0xbfb8aa3b, v41
	v_mul_f32_e32 v50, 0xbfb8aa3b, v42
	v_mul_f32_e32 v51, 0xbfb8aa3b, v43
	v_exp_f32_e32 v48, v48
	v_exp_f32_e32 v49, v49
	v_exp_f32_e32 v50, v50
	v_exp_f32_e32 v51, v51
	v_add_f32_e32 v54, 1.0, v54
	v_add_f32_e32 v55, 1.0, v55
	v_rcp_f32_e32 v54, v54
	v_rcp_f32_e32 v55, v55
	v_add_f32_e32 v56, 1.0, v56
	v_add_f32_e32 v57, 1.0, v57
	v_add_f32_e32 v48, 1.0, v48
	v_add_f32_e32 v49, 1.0, v49
	v_add_f32_e32 v50, 1.0, v50
	v_add_f32_e32 v51, 1.0, v51
	v_rcp_f32_e32 v56, v56
	v_rcp_f32_e32 v57, v57
	v_rcp_f32_e32 v48, v48
	v_rcp_f32_e32 v49, v49
	v_rcp_f32_e32 v50, v50
	v_rcp_f32_e32 v51, v51
	v_pk_mul_f32 v[44:45], v[44:45], v[54:55]
	v_pk_mul_f32 v[36:37], v[36:37], v[160:161] op_sel_hi:[1,0]
	v_pk_mul_f32 v[46:47], v[46:47], v[56:57]
	v_pk_mul_f32 v[38:39], v[38:39], v[160:161] op_sel_hi:[1,0]
	v_pk_mul_f32 v[36:37], v[36:37], v[44:45]
	v_pk_mul_f32 v[40:41], v[40:41], v[48:49]
	v_pk_mul_f32 v[42:43], v[42:43], v[50:51]
	v_pk_mul_f32 v[32:33], v[32:33], v[160:161] op_sel_hi:[1,0]
	v_pk_mul_f32 v[34:35], v[34:35], v[160:161] op_sel_hi:[1,0]
	v_pk_mul_f32 v[38:39], v[38:39], v[46:47]
	v_pk_mul_f32 v[42:43], v[34:35], v[42:43]
	v_pk_mul_f32 v[34:35], v[32:33], v[40:41]
	v_cvt_pk_bf16_f32 v32, v36, v37
	v_mad_i64_i32 v[36:37], s[46:47], v150, s60, v[112:113]
	v_pk_mul_f32 v[28:29], v[28:29], v[156:157] op_sel_hi:[1,0]
	v_cvt_pk_bf16_f32 v33, v38, v39
	v_cvt_pk_bf16_f32 v34, v34, v35
	v_cvt_pk_bf16_f32 v35, v42, v43
	v_pk_mul_f32 v[30:31], v[30:31], v[156:157] op_sel_hi:[1,0]
	v_mul_f32_e32 v38, 0xbfb8aa3b, v28
	v_mul_f32_e32 v39, 0xbfb8aa3b, v29
	v_lshl_add_u64 v[36:37], v[36:37], 0, v[114:115]
	v_pk_mul_f32 v[24:25], v[24:25], v[156:157] op_sel_hi:[1,0]
	v_pk_mul_f32 v[26:27], v[26:27], v[156:157] op_sel_hi:[1,0]
	v_exp_f32_e32 v38, v38
	v_exp_f32_e32 v39, v39
	v_mul_f32_e32 v40, 0xbfb8aa3b, v30
	v_mul_f32_e32 v41, 0xbfb8aa3b, v31
	global_store_dwordx4 v[36:37], v[32:35], off nt
	v_exp_f32_e32 v40, v40
	v_exp_f32_e32 v41, v41
	v_mul_f32_e32 v32, 0xbfb8aa3b, v24
	v_mul_f32_e32 v33, 0xbfb8aa3b, v25
	v_mul_f32_e32 v34, 0xbfb8aa3b, v26
	v_mul_f32_e32 v35, 0xbfb8aa3b, v27
	v_exp_f32_e32 v32, v32
	v_exp_f32_e32 v33, v33
	v_exp_f32_e32 v34, v34
	v_exp_f32_e32 v35, v35
	v_add_f32_e32 v38, 1.0, v38
	v_add_f32_e32 v39, 1.0, v39
	v_rcp_f32_e32 v38, v38
	v_rcp_f32_e32 v39, v39
	v_add_f32_e32 v40, 1.0, v40
	v_add_f32_e32 v41, 1.0, v41
	v_add_f32_e32 v32, 1.0, v32
	v_add_f32_e32 v33, 1.0, v33
	v_add_f32_e32 v34, 1.0, v34
	v_add_f32_e32 v35, 1.0, v35
	v_rcp_f32_e32 v40, v40
	v_rcp_f32_e32 v41, v41
	v_rcp_f32_e32 v32, v32
	v_rcp_f32_e32 v33, v33
	v_rcp_f32_e32 v34, v34
	v_rcp_f32_e32 v35, v35
	v_pk_mul_f32 v[28:29], v[28:29], v[38:39]
	v_pk_mul_f32 v[20:21], v[20:21], v[156:157] op_sel_hi:[1,0]
	v_pk_mul_f32 v[30:31], v[30:31], v[40:41]
	v_pk_mul_f32 v[22:23], v[22:23], v[156:157] op_sel_hi:[1,0]
	v_pk_mul_f32 v[20:21], v[20:21], v[28:29]
	v_pk_mul_f32 v[24:25], v[24:25], v[32:33]
	v_pk_mul_f32 v[26:27], v[26:27], v[34:35]
	v_pk_mul_f32 v[16:17], v[16:17], v[156:157] op_sel_hi:[1,0]
	v_pk_mul_f32 v[18:19], v[18:19], v[156:157] op_sel_hi:[1,0]
	v_pk_mul_f32 v[22:23], v[22:23], v[30:31]
	v_pk_mul_f32 v[26:27], v[18:19], v[26:27]
	v_pk_mul_f32 v[18:19], v[16:17], v[24:25]
	v_cvt_pk_bf16_f32 v16, v20, v21
	v_mad_i64_i32 v[20:21], s[46:47], v148, s60, v[112:113]
	v_pk_mul_f32 v[12:13], v[12:13], v[152:153] op_sel_hi:[1,0]
	v_cvt_pk_bf16_f32 v17, v22, v23
	v_cvt_pk_bf16_f32 v18, v18, v19
	v_cvt_pk_bf16_f32 v19, v26, v27
	v_lshl_add_u64 v[20:21], v[20:21], 0, v[114:115]
	v_mul_f32_e32 v22, 0xbfb8aa3b, v12
	v_mul_f32_e32 v23, 0xbfb8aa3b, v13
	v_pk_mul_f32 v[8:9], v[8:9], v[152:153] op_sel_hi:[1,0]
	v_pk_mul_f32 v[10:11], v[10:11], v[152:153] op_sel_hi:[1,0]
	v_exp_f32_e32 v22, v22
	v_exp_f32_e32 v23, v23
	global_store_dwordx4 v[20:21], v[16:19], off nt
	v_pk_mul_f32 v[14:15], v[14:15], v[152:153] op_sel_hi:[1,0]
	v_add_f32_e32 v22, 1.0, v22
	v_mul_f32_e32 v16, 0xbfb8aa3b, v8
	v_mul_f32_e32 v17, 0xbfb8aa3b, v9
	v_mul_f32_e32 v18, 0xbfb8aa3b, v10
	v_mul_f32_e32 v19, 0xbfb8aa3b, v11
	v_exp_f32_e32 v16, v16
	v_exp_f32_e32 v17, v17
	v_exp_f32_e32 v18, v18
	v_exp_f32_e32 v19, v19
	v_mul_f32_e32 v24, 0xbfb8aa3b, v14
	v_mul_f32_e32 v25, 0xbfb8aa3b, v15
	v_exp_f32_e32 v24, v24
	v_exp_f32_e32 v25, v25
	v_add_f32_e32 v23, 1.0, v23
	v_rcp_f32_e32 v22, v22
	v_rcp_f32_e32 v23, v23
	v_add_f32_e32 v16, 1.0, v16
	v_add_f32_e32 v17, 1.0, v17
	v_add_f32_e32 v18, 1.0, v18
	v_add_f32_e32 v19, 1.0, v19
	v_rcp_f32_e32 v16, v16
	v_rcp_f32_e32 v17, v17
	v_rcp_f32_e32 v18, v18
	v_rcp_f32_e32 v19, v19
	v_add_f32_e32 v24, 1.0, v24
	v_add_f32_e32 v25, 1.0, v25
	v_rcp_f32_e32 v24, v24
	v_rcp_f32_e32 v25, v25
	v_pk_mul_f32 v[12:13], v[12:13], v[22:23]
	v_pk_mul_f32 v[4:5], v[4:5], v[152:153] op_sel_hi:[1,0]
	v_pk_mul_f32 v[8:9], v[8:9], v[16:17]
	v_pk_mul_f32 v[4:5], v[4:5], v[12:13]
	v_pk_mul_f32 v[10:11], v[10:11], v[18:19]
	v_pk_mul_f32 v[0:1], v[0:1], v[152:153] op_sel_hi:[1,0]
	v_pk_mul_f32 v[2:3], v[2:3], v[152:153] op_sel_hi:[1,0]
	v_pk_mul_f32 v[14:15], v[14:15], v[24:25]
	v_pk_mul_f32 v[10:11], v[2:3], v[10:11]
	v_pk_mul_f32 v[2:3], v[0:1], v[8:9]
	v_cvt_pk_bf16_f32 v0, v4, v5
	v_mad_i64_i32 v[4:5], s[46:47], v146, s60, v[112:113]
	v_pk_mul_f32 v[6:7], v[6:7], v[152:153] op_sel_hi:[1,0]
	v_lshl_add_u64 v[4:5], v[4:5], 0, v[114:115]
	v_pk_mul_f32 v[6:7], v[6:7], v[14:15]
	s_nop 0
	v_cvt_pk_bf16_f32 v1, v6, v7
	v_cvt_pk_bf16_f32 v2, v2, v3
	v_cvt_pk_bf16_f32 v3, v10, v11
	global_store_dwordx4 v[4:5], v[0:3], off nt
	s_cbranch_vccnz .LBB0_1584
	s_andn2_b64 vcc, exec, s[14:15]
	s_cbranch_vccnz .LBB0_1583
	s_barrier
	s_branch .LBB0_1583

; __device__ __forceinline__ float row_part(const float* ss, int row, int fq) { const f32x4 a = ((const f32x4*)(ss + (size_t)row * 16))[fq]; return (a[0] + a[1]) + (a[2] + a[3]); }
; __device__ __forceinline__ float row_finish(float t) { t += shx(t, 16); t += shx(t, 32); return __builtin_amdgcn_rsqf(t * (1.0f / 1024.0f) + RMS_EPS); }
;     __device__ __forceinline__ void operator()(const f32x4 (&acc)[2][2][4][2], const Unit& u, int wr, int wc, int fr, int fq) const {
;         const int col0 = u.pn * 128 + 32 * wc + 8 * fq;
;         float rs[2][4];
; #pragma unroll
;         for (int ai = 0; ai < 2; ++ai)
; #pragma unroll
;             for (int m = 0; m < 4; ++m) rs[ai][m] = row_part(ss, u.pm * BM + ai * HALF + wr * 64 + m * 16 + fr, fq);
; #pragma unroll
;         for (int ai = 0; ai < 2; ++ai)
; #pragma unroll
;             for (int m = 0; m < 4; ++m) rs[ai][m] = row_finish(rs[ai][m]);
.LBB0_2043:
	v_lshl_add_u32 v170, s24, 8, v153
	v_ashrrev_i32_e32 v171, 31, v170
	v_or_b32_e32 v166, 16, v170
	v_lshlrev_b64 v[146:147], 6, v[170:171]
	v_ashrrev_i32_e32 v167, 31, v166
	v_lshl_add_u64 v[146:147], v[136:137], 0, v[146:147]
	v_lshlrev_b64 v[148:149], 6, v[166:167]
	v_lshl_add_u64 v[148:149], v[136:137], 0, v[148:149]
	ds_read_b128 v[176:179], v239
	ds_read_b128 v[180:183], v239 offset:1024
	v_or_b32_e32 v162, 32, v170
	v_ashrrev_i32_e32 v163, 31, v162
	v_or_b32_e32 v158, 48, v170
	v_lshlrev_b64 v[146:147], 6, v[162:163]
	v_ashrrev_i32_e32 v159, 31, v158
	v_lshl_add_u64 v[146:147], v[136:137], 0, v[146:147]
	v_lshlrev_b64 v[148:149], 6, v[158:159]
	v_lshl_add_u64 v[148:149], v[136:137], 0, v[148:149]
	ds_read_b128 v[184:187], v239 offset:2048
	ds_read_b128 v[188:191], v239 offset:3072
	v_add_u32_e32 v154, 0x80, v170
	v_ashrrev_i32_e32 v155, 31, v154
	v_add_u32_e32 v150, 0x90, v170
	v_lshlrev_b64 v[146:147], 6, v[154:155]
	v_ashrrev_i32_e32 v151, 31, v150
	v_lshl_add_u64 v[146:147], v[136:137], 0, v[146:147]
	v_lshlrev_b64 v[148:149], 6, v[150:151]
	v_lshl_add_u64 v[148:149], v[136:137], 0, v[148:149]
	ds_read_b128 v[192:195], v239 offset:8192
	ds_read_b128 v[196:199], v239 offset:9216
	v_add_u32_e32 v148, 0xa0, v170
	v_ashrrev_i32_e32 v149, 31, v148
	v_lshlrev_b64 v[146:147], 6, v[148:149]
	v_lshl_add_u64 v[146:147], v[136:137], 0, v[146:147]
	ds_read_b128 v[202:205], v239 offset:10240
	v_add_u32_e32 v146, 0xb0, v170
	v_ashrrev_i32_e32 v147, 31, v146
	v_lshlrev_b64 v[206:207], 6, v[146:147]
	v_lshl_add_u64 v[206:207], v[136:137], 0, v[206:207]
	ds_read_b128 v[206:209], v239 offset:11264
	v_mov_b32_e32 v147, v201
	v_mov_b32_e32 v149, v201
	v_lshlrev_b32_e32 v147, 2, v147
	v_mov_b32_e32 v151, v201
	v_xor_b32_e32 v147, 64, v147
	s_andn2_b64 vcc, exec, s[6:7]
	v_lshlrev_b32_e32 v151, 2, v151
	v_xor_b32_e32 v151, 64, v151
	v_lshlrev_b32_e32 v149, 2, v149
	v_xor_b32_e32 v149, 0x80, v149
	s_mov_b64 s[6:7], -1
	s_waitcnt lgkmcnt(0)
	v_mov_b32_e32 v210, v177
	v_mov_b32_e32 v211, v178
	v_mov_b32_e32 v177, v179
	v_pk_add_f32 v[176:177], v[210:211], v[176:177]
	v_mov_b32_e32 v178, v181
	v_add_f32_e32 v152, v176, v177
	v_mov_b32_e32 v179, v182
	v_mov_b32_e32 v181, v183
	v_mov_b32_e32 v147, v152
	s_nop 1
	v_permlane16_swap_b32_e32 v147, v152
	v_pk_add_f32 v[176:177], v[178:179], v[180:181]
	v_mov_b32_e32 v182, v185
	v_add_f32_e32 v155, v176, v177
	v_mov_b32_e32 v151, v155
	s_nop 1
	v_permlane16_swap_b32_e32 v151, v155
	s_waitcnt lgkmcnt(0)
	v_add_f32_e32 v147, v152, v147
	v_mov_b32_e32 v152, v201
	v_mov_b32_e32 v149, v147
	s_nop 1
	v_permlane32_swap_b32_e32 v149, v147
	s_waitcnt lgkmcnt(0)
	v_add_f32_e32 v151, v155, v151
	v_lshlrev_b32_e32 v152, 2, v152
	v_xor_b32_e32 v152, 0x80, v152
	v_mov_b32_e32 v152, v151
	s_nop 1
	v_permlane32_swap_b32_e32 v152, v151
	s_waitcnt lgkmcnt(0)
	v_add_f32_e32 v147, v147, v149
	v_mov_b32_e32 v149, v201
	v_mov_b32_e32 v183, v186
	v_mov_b32_e32 v185, v187
	v_pk_add_f32 v[178:179], v[182:183], v[184:185]
	v_fmamk_f32 v147, v147, 0x3a800000, v175
	v_lshlrev_b32_e32 v149, 2, v149
	v_add_f32_e32 v156, v178, v179
	v_rsq_f32_e32 v176, v147
	s_waitcnt lgkmcnt(0)
	v_add_f32_e32 v147, v151, v152
	v_xor_b32_e32 v149, 64, v149
	v_mov_b32_e32 v151, v201
	v_mov_b32_e32 v152, v201
	v_mov_b32_e32 v186, v189
	v_mov_b32_e32 v187, v190
	v_mov_b32_e32 v189, v191
	v_mov_b32_e32 v149, v156
	s_nop 1
	v_permlane16_swap_b32_e32 v149, v156
	v_pk_add_f32 v[180:181], v[186:187], v[188:189]
	v_lshlrev_b32_e32 v152, 2, v152
	v_add_f32_e32 v159, v180, v181
	v_xor_b32_e32 v152, 64, v152
	v_mov_b32_e32 v152, v159
	s_nop 1
	v_permlane16_swap_b32_e32 v152, v159
	s_waitcnt lgkmcnt(0)
	v_add_f32_e32 v149, v156, v149
	v_lshlrev_b32_e32 v151, 2, v151
	v_mov_b32_e32 v156, v201
	v_xor_b32_e32 v151, 0x80, v151
	v_mov_b32_e32 v151, v149
	s_nop 1
	v_permlane32_swap_b32_e32 v151, v149
	v_lshlrev_b32_e32 v156, 2, v156
	s_waitcnt lgkmcnt(0)
	v_add_f32_e32 v152, v159, v152
	v_xor_b32_e32 v156, 0x80, v156
	v_mov_b32_e32 v156, v152
	s_nop 1
	v_permlane32_swap_b32_e32 v156, v152
	v_fmamk_f32 v147, v147, 0x3a800000, v175
	v_rsq_f32_e32 v174, v147
	s_waitcnt lgkmcnt(0)
	v_add_f32_e32 v147, v149, v151
	v_mov_b32_e32 v149, v201
	v_mov_b32_e32 v190, v193
	v_mov_b32_e32 v191, v194
	v_mov_b32_e32 v193, v195
	v_fmamk_f32 v147, v147, 0x3a800000, v175
	v_pk_add_f32 v[182:183], v[190:191], v[192:193]
	v_rsq_f32_e32 v172, v147
	s_waitcnt lgkmcnt(0)
	v_add_f32_e32 v147, v152, v156
	v_lshlrev_b32_e32 v149, 2, v149
	v_mov_b32_e32 v151, v201
	v_mov_b32_e32 v152, v201
	v_mov_b32_e32 v194, v197
	v_mov_b32_e32 v195, v198
	v_mov_b32_e32 v197, v199
	v_add_f32_e32 v160, v182, v183
	v_xor_b32_e32 v149, 64, v149
	v_pk_add_f32 v[184:185], v[194:195], v[196:197]
	v_mov_b32_e32 v149, v160
	s_nop 1
	v_permlane16_swap_b32_e32 v149, v160
	v_lshlrev_b32_e32 v152, 2, v152
	v_add_f32_e32 v163, v184, v185
	v_xor_b32_e32 v152, 64, v152
	v_mov_b32_e32 v152, v163
	s_nop 1
	v_permlane16_swap_b32_e32 v152, v163
	v_lshlrev_b32_e32 v151, 2, v151
	v_mov_b32_e32 v156, v201
	s_waitcnt lgkmcnt(0)
	v_add_f32_e32 v149, v160, v149
	v_xor_b32_e32 v151, 0x80, v151
	v_mov_b32_e32 v151, v149
	s_nop 1
	v_permlane32_swap_b32_e32 v151, v149
	v_lshlrev_b32_e32 v156, 2, v156
	s_waitcnt lgkmcnt(0)
	v_add_f32_e32 v152, v163, v152
	v_xor_b32_e32 v156, 0x80, v156
	v_mov_b32_e32 v156, v152
	s_nop 1
	v_permlane32_swap_b32_e32 v156, v152
	v_fmamk_f32 v147, v147, 0x3a800000, v175
	v_rsq_f32_e32 v168, v147
	s_waitcnt lgkmcnt(0)
	v_add_f32_e32 v147, v149, v151
	v_fmamk_f32 v147, v147, 0x3a800000, v175
	v_rsq_f32_e32 v164, v147
	s_waitcnt lgkmcnt(0)
; __device__ __forceinline__ float row_finish(float t) { t += shx(t, 16); t += shx(t, 32); return __builtin_amdgcn_rsqf(t * (1.0f / 1024.0f) + RMS_EPS); }
; __device__ __forceinline__ f32x4 silu4(f32x4 v) { return (f32x4){silu_f(v[0]), silu_f(v[1]), silu_f(v[2]), silu_f(v[3])}; }
; __device__ __forceinline__ u32x4 pack8(f32x4 a, f32x4 b) { u32x4 w; w.x = cvt_pk_bf16(a[0], a[1]); w.y = cvt_pk_bf16(a[2], a[3]); w.z = cvt_pk_bf16(b[0], b[1]); w.w = cvt_pk_bf16(b[2], b[3]); return w; }
;     __device__ __forceinline__ void operator()(const f32x4 (&acc)[2][2][4][2], const Unit& u, int wr, int wc, int fr, int fq) const {
;     ...
;             for (int m = 0; m < 4; ++m) rs[ai][m] = row_finish(rs[ai][m]);
; #pragma unroll
;         for (int ai = 0; ai < 2; ++ai)
; #pragma unroll
;             for (int m = 0; m < 4; ++m) {
;                 const int row = u.pm * BM + ai * HALF + wr * 64 + m * 16 + fr;
;                 const float rstd = rs[ai][m];
;                 const f32x4 a0 = silu4(acc[ai][0][m][0] * rstd) * (acc[ai][1][m][0] * rstd);
;                 const f32x4 a1 = silu4(acc[ai][0][m][1] * rstd) * (acc[ai][1][m][1] * rstd);
;                 *(u32x4*)(ACT + (size_t)row * 2816 + col0) = pack8(a0, a1);
	v_add_f32_e32 v147, v152, v156
	v_mov_b32_e32 v149, v201
	v_mov_b32_e32 v151, v201
	v_mov_b32_e32 v152, v201
	v_mov_b32_e32 v198, v203
	v_mov_b32_e32 v199, v204
	v_mov_b32_e32 v203, v205
	v_mov_b32_e32 v204, v207
	v_mov_b32_e32 v205, v208
	v_mov_b32_e32 v207, v209
	v_pk_add_f32 v[188:189], v[204:205], v[206:207]
	v_lshlrev_b32_e32 v152, 2, v152
	v_pk_add_f32 v[186:187], v[198:199], v[202:203]
	v_add_f32_e32 v155, v188, v189
	v_lshlrev_b32_e32 v149, 2, v149
	v_xor_b32_e32 v152, 64, v152
	v_add_f32_e32 v167, v186, v187
	v_xor_b32_e32 v149, 64, v149
	v_mov_b32_e32 v152, v155
	s_nop 1
	v_permlane16_swap_b32_e32 v152, v155
	v_mov_b32_e32 v149, v167
	s_nop 1
	v_permlane16_swap_b32_e32 v149, v167
	v_lshlrev_b32_e32 v151, 2, v151
	v_xor_b32_e32 v151, 0x80, v151
	v_fmamk_f32 v147, v147, 0x3a800000, v175
	s_waitcnt lgkmcnt(0)
	v_add_f32_e32 v152, v155, v152
	v_mov_b32_e32 v155, v201
	s_waitcnt lgkmcnt(0)
	v_add_f32_e32 v149, v167, v149
	v_mov_b32_e32 v151, v149
	s_nop 1
	v_permlane32_swap_b32_e32 v151, v149
	v_lshlrev_b32_e32 v155, 2, v155
	v_xor_b32_e32 v155, 0x80, v155
	v_mov_b32_e32 v155, v152
	s_nop 1
	v_permlane32_swap_b32_e32 v155, v152
	v_rsq_f32_e32 v160, v147
	s_waitcnt lgkmcnt(0)
	v_add_f32_e32 v147, v149, v151
	v_fmamk_f32 v147, v147, 0x3a800000, v175
	v_rsq_f32_e32 v156, v147
	s_waitcnt lgkmcnt(0)
	v_add_f32_e32 v147, v152, v155
	v_fmamk_f32 v147, v147, 0x3a800000, v175
	v_pk_mul_f32 v[124:125], v[124:125], v[176:177] op_sel_hi:[1,0]
	v_rsq_f32_e32 v152, v147
	v_mul_f32_e32 v147, 0xbfb8aa3b, v124
	v_exp_f32_e32 v147, v147
	v_mul_f32_e32 v149, 0xbfb8aa3b, v125
	v_exp_f32_e32 v149, v149
	v_pk_mul_f32 v[126:127], v[126:127], v[176:177] op_sel_hi:[1,0]
	v_add_f32_e32 v147, 1.0, v147
	v_rcp_f32_e32 v178, v147
	v_add_f32_e32 v147, 1.0, v149
	v_mul_f32_e32 v149, 0xbfb8aa3b, v126
	v_exp_f32_e32 v149, v149
	v_mul_f32_e32 v151, 0xbfb8aa3b, v127
	v_exp_f32_e32 v151, v151
	v_rcp_f32_e32 v179, v147
	v_add_f32_e32 v147, 1.0, v149
	v_rcp_f32_e32 v180, v147
	v_add_f32_e32 v147, 1.0, v151
	v_pk_mul_f32 v[120:121], v[120:121], v[176:177] op_sel_hi:[1,0]
	v_rcp_f32_e32 v181, v147
	v_mul_f32_e32 v147, 0xbfb8aa3b, v120
	v_exp_f32_e32 v147, v147
	v_mul_f32_e32 v149, 0xbfb8aa3b, v121
	v_exp_f32_e32 v149, v149
	v_pk_mul_f32 v[122:123], v[122:123], v[176:177] op_sel_hi:[1,0]
	v_add_f32_e32 v147, 1.0, v147
	v_pk_mul_f32 v[124:125], v[124:125], v[178:179]
	v_rcp_f32_e32 v178, v147
	v_add_f32_e32 v147, 1.0, v149
	v_mul_f32_e32 v149, 0xbfb8aa3b, v122
	v_exp_f32_e32 v149, v149
	v_mul_f32_e32 v151, 0xbfb8aa3b, v123
	v_exp_f32_e32 v151, v151
	v_rcp_f32_e32 v179, v147
	v_add_f32_e32 v147, 1.0, v149
	v_pk_mul_f32 v[126:127], v[126:127], v[180:181]
	v_rcp_f32_e32 v180, v147
	v_add_f32_e32 v147, 1.0, v151
	v_rcp_f32_e32 v181, v147
	v_pk_mul_f32 v[116:117], v[116:117], v[176:177] op_sel_hi:[1,0]
	v_pk_mul_f32 v[118:119], v[118:119], v[176:177] op_sel_hi:[1,0]
	v_pk_mul_f32 v[120:121], v[120:121], v[178:179]
	v_pk_mul_f32 v[112:113], v[112:113], v[176:177] op_sel_hi:[1,0]
	v_lshl_or_b32 v182, s48, 7, v161
	v_pk_mul_f32 v[118:119], v[118:119], v[126:127]
	v_pk_mul_f32 v[116:117], v[116:117], v[124:125]
	v_pk_mul_f32 v[122:123], v[122:123], v[180:181]
	v_pk_mul_f32 v[114:115], v[114:115], v[176:177] op_sel_hi:[1,0]
	v_pk_mul_f32 v[112:113], v[112:113], v[120:121]
	v_ashrrev_i32_e32 v183, 31, v182
	v_pk_mul_f32 v[114:115], v[114:115], v[122:123]
	v_cvt_pk_bf16_f32 v116, v116, v117
	v_cvt_pk_bf16_f32 v117, v118, v119
	v_cvt_pk_bf16_f32 v118, v112, v113
	v_mov_b64_e32 v[112:113], s[10:11]
	v_cvt_pk_bf16_f32 v119, v114, v115
	v_mad_i64_i32 v[120:121], s[26:27], v170, s47, v[112:113]
	v_lshlrev_b64 v[114:115], 1, v[182:183]
	v_pk_mul_f32 v[108:109], v[108:109], v[174:175] op_sel_hi:[1,0]
	v_pk_mul_f32 v[110:111], v[110:111], v[174:175] op_sel_hi:[1,0]
	v_mul_f32_e32 v122, 0xbfb8aa3b, v108
	v_mul_f32_e32 v123, 0xbfb8aa3b, v109
	v_lshl_add_u64 v[120:121], v[120:121], 0, v[114:115]
	v_pk_mul_f32 v[104:105], v[104:105], v[174:175] op_sel_hi:[1,0]
	v_pk_mul_f32 v[106:107], v[106:107], v[174:175] op_sel_hi:[1,0]
	v_exp_f32_e32 v122, v122
	v_exp_f32_e32 v123, v123
	v_mul_f32_e32 v124, 0xbfb8aa3b, v110
	v_mul_f32_e32 v125, 0xbfb8aa3b, v111
	global_store_dwordx4 v[120:121], v[116:119], off nt
	v_exp_f32_e32 v124, v124
	v_exp_f32_e32 v125, v125
	v_mul_f32_e32 v116, 0xbfb8aa3b, v104
	v_mul_f32_e32 v117, 0xbfb8aa3b, v105
	v_mul_f32_e32 v118, 0xbfb8aa3b, v106
	v_mul_f32_e32 v119, 0xbfb8aa3b, v107
	v_exp_f32_e32 v116, v116
	v_exp_f32_e32 v117, v117
	v_exp_f32_e32 v118, v118
	v_exp_f32_e32 v119, v119
	v_add_f32_e32 v122, 1.0, v122
	v_add_f32_e32 v123, 1.0, v123
	v_rcp_f32_e32 v122, v122
	v_rcp_f32_e32 v123, v123
	v_add_f32_e32 v124, 1.0, v124
	v_add_f32_e32 v125, 1.0, v125
	v_add_f32_e32 v116, 1.0, v116
	v_add_f32_e32 v117, 1.0, v117
	v_add_f32_e32 v118, 1.0, v118
	v_add_f32_e32 v119, 1.0, v119
	v_rcp_f32_e32 v124, v124
	v_rcp_f32_e32 v125, v125
	v_rcp_f32_e32 v116, v116
	v_rcp_f32_e32 v117, v117
	v_rcp_f32_e32 v118, v118
	v_rcp_f32_e32 v119, v119
	v_pk_mul_f32 v[108:109], v[108:109], v[122:123]
	v_pk_mul_f32 v[100:101], v[100:101], v[174:175] op_sel_hi:[1,0]
	v_pk_mul_f32 v[110:111], v[110:111], v[124:125]
	v_pk_mul_f32 v[102:103], v[102:103], v[174:175] op_sel_hi:[1,0]
	v_pk_mul_f32 v[100:101], v[100:101], v[108:109]
	v_pk_mul_f32 v[104:105], v[104:105], v[116:117]
	v_pk_mul_f32 v[106:107], v[106:107], v[118:119]
	v_pk_mul_f32 v[96:97], v[96:97], v[174:175] op_sel_hi:[1,0]
	v_pk_mul_f32 v[98:99], v[98:99], v[174:175] op_sel_hi:[1,0]
	v_pk_mul_f32 v[102:103], v[102:103], v[110:111]
	v_pk_mul_f32 v[106:107], v[98:99], v[106:107]
	v_pk_mul_f32 v[98:99], v[96:97], v[104:105]
; __device__ __forceinline__ f32x4 silu4(f32x4 v) { return (f32x4){silu_f(v[0]), silu_f(v[1]), silu_f(v[2]), silu_f(v[3])}; }
; __device__ __forceinline__ u32x4 pack8(f32x4 a, f32x4 b) { u32x4 w; w.x = cvt_pk_bf16(a[0], a[1]); w.y = cvt_pk_bf16(a[2], a[3]); w.z = cvt_pk_bf16(b[0], b[1]); w.w = cvt_pk_bf16(b[2], b[3]); return w; }
;     __device__ __forceinline__ void operator()(const f32x4 (&acc)[2][2][4][2], const Unit& u, int wr, int wc, int fr, int fq) const {
;     ...
;         for (int ai = 0; ai < 2; ++ai)
; #pragma unroll
;             for (int m = 0; m < 4; ++m) {
;                 const int row = u.pm * BM + ai * HALF + wr * 64 + m * 16 + fr;
;                 const float rstd = rs[ai][m];
;                 const f32x4 a0 = silu4(acc[ai][0][m][0] * rstd) * (acc[ai][1][m][0] * rstd);
;                 const f32x4 a1 = silu4(acc[ai][0][m][1] * rstd) * (acc[ai][1][m][1] * rstd);
;                 *(u32x4*)(ACT + (size_t)row * 2816 + col0) = pack8(a0, a1);
;             }
	v_cvt_pk_bf16_f32 v96, v100, v101
	v_mad_i64_i32 v[100:101], s[26:27], v166, s47, v[112:113]
	v_pk_mul_f32 v[92:93], v[92:93], v[172:173] op_sel_hi:[1,0]
	v_cvt_pk_bf16_f32 v97, v102, v103
	v_cvt_pk_bf16_f32 v98, v98, v99
	v_cvt_pk_bf16_f32 v99, v106, v107
	v_pk_mul_f32 v[94:95], v[94:95], v[172:173] op_sel_hi:[1,0]
	v_mul_f32_e32 v102, 0xbfb8aa3b, v92
	v_mul_f32_e32 v103, 0xbfb8aa3b, v93
	v_lshl_add_u64 v[100:101], v[100:101], 0, v[114:115]
	v_pk_mul_f32 v[88:89], v[88:89], v[172:173] op_sel_hi:[1,0]
	v_pk_mul_f32 v[90:91], v[90:91], v[172:173] op_sel_hi:[1,0]
	v_exp_f32_e32 v102, v102
	v_exp_f32_e32 v103, v103
	v_mul_f32_e32 v104, 0xbfb8aa3b, v94
	v_mul_f32_e32 v105, 0xbfb8aa3b, v95
	global_store_dwordx4 v[100:101], v[96:99], off nt
	v_exp_f32_e32 v104, v104
	v_exp_f32_e32 v105, v105
	v_mul_f32_e32 v96, 0xbfb8aa3b, v88
	v_mul_f32_e32 v97, 0xbfb8aa3b, v89
	v_mul_f32_e32 v98, 0xbfb8aa3b, v90
	v_mul_f32_e32 v99, 0xbfb8aa3b, v91
	v_exp_f32_e32 v96, v96
	v_exp_f32_e32 v97, v97
	v_exp_f32_e32 v98, v98
	v_exp_f32_e32 v99, v99
	v_add_f32_e32 v102, 1.0, v102
	v_add_f32_e32 v103, 1.0, v103
	v_rcp_f32_e32 v102, v102
	v_rcp_f32_e32 v103, v103
	v_add_f32_e32 v104, 1.0, v104
	v_add_f32_e32 v105, 1.0, v105
	v_add_f32_e32 v96, 1.0, v96
	v_add_f32_e32 v97, 1.0, v97
	v_add_f32_e32 v98, 1.0, v98
	v_add_f32_e32 v99, 1.0, v99
	v_rcp_f32_e32 v104, v104
	v_rcp_f32_e32 v105, v105
	v_rcp_f32_e32 v96, v96
	v_rcp_f32_e32 v97, v97
	v_rcp_f32_e32 v98, v98
	v_rcp_f32_e32 v99, v99
	v_pk_mul_f32 v[92:93], v[92:93], v[102:103]
	v_pk_mul_f32 v[84:85], v[84:85], v[172:173] op_sel_hi:[1,0]
	v_pk_mul_f32 v[94:95], v[94:95], v[104:105]
	v_pk_mul_f32 v[86:87], v[86:87], v[172:173] op_sel_hi:[1,0]
	v_pk_mul_f32 v[84:85], v[84:85], v[92:93]
	v_pk_mul_f32 v[88:89], v[88:89], v[96:97]
	v_pk_mul_f32 v[90:91], v[90:91], v[98:99]
	v_pk_mul_f32 v[80:81], v[80:81], v[172:173] op_sel_hi:[1,0]
	v_pk_mul_f32 v[82:83], v[82:83], v[172:173] op_sel_hi:[1,0]
	v_pk_mul_f32 v[86:87], v[86:87], v[94:95]
	v_pk_mul_f32 v[90:91], v[82:83], v[90:91]
	v_pk_mul_f32 v[82:83], v[80:81], v[88:89]
	v_cvt_pk_bf16_f32 v80, v84, v85
	v_mad_i64_i32 v[84:85], s[26:27], v162, s47, v[112:113]
	v_pk_mul_f32 v[76:77], v[76:77], v[168:169] op_sel_hi:[1,0]
	v_cvt_pk_bf16_f32 v81, v86, v87
	v_cvt_pk_bf16_f32 v82, v82, v83
	v_cvt_pk_bf16_f32 v83, v90, v91
	v_pk_mul_f32 v[78:79], v[78:79], v[168:169] op_sel_hi:[1,0]
	v_mul_f32_e32 v86, 0xbfb8aa3b, v76
	v_mul_f32_e32 v87, 0xbfb8aa3b, v77
	v_lshl_add_u64 v[84:85], v[84:85], 0, v[114:115]
	v_pk_mul_f32 v[72:73], v[72:73], v[168:169] op_sel_hi:[1,0]
	v_pk_mul_f32 v[74:75], v[74:75], v[168:169] op_sel_hi:[1,0]
	v_exp_f32_e32 v86, v86
	v_exp_f32_e32 v87, v87
	v_mul_f32_e32 v88, 0xbfb8aa3b, v78
	v_mul_f32_e32 v89, 0xbfb8aa3b, v79
	global_store_dwordx4 v[84:85], v[80:83], off nt
	v_exp_f32_e32 v88, v88
	v_exp_f32_e32 v89, v89
	v_mul_f32_e32 v80, 0xbfb8aa3b, v72
	v_mul_f32_e32 v81, 0xbfb8aa3b, v73
	v_mul_f32_e32 v82, 0xbfb8aa3b, v74
	v_mul_f32_e32 v83, 0xbfb8aa3b, v75
	v_exp_f32_e32 v80, v80
	v_exp_f32_e32 v81, v81
	v_exp_f32_e32 v82, v82
	v_exp_f32_e32 v83, v83
	v_add_f32_e32 v86, 1.0, v86
	v_add_f32_e32 v87, 1.0, v87
	v_rcp_f32_e32 v86, v86
	v_rcp_f32_e32 v87, v87
	v_add_f32_e32 v88, 1.0, v88
	v_add_f32_e32 v89, 1.0, v89
	v_add_f32_e32 v80, 1.0, v80
	v_add_f32_e32 v81, 1.0, v81
	v_add_f32_e32 v82, 1.0, v82
	v_add_f32_e32 v83, 1.0, v83
	v_rcp_f32_e32 v88, v88
	v_rcp_f32_e32 v89, v89
	v_rcp_f32_e32 v80, v80
	v_rcp_f32_e32 v81, v81
	v_rcp_f32_e32 v82, v82
	v_rcp_f32_e32 v83, v83
	v_pk_mul_f32 v[76:77], v[76:77], v[86:87]
	v_pk_mul_f32 v[68:69], v[68:69], v[168:169] op_sel_hi:[1,0]
	v_pk_mul_f32 v[78:79], v[78:79], v[88:89]
	v_pk_mul_f32 v[70:71], v[70:71], v[168:169] op_sel_hi:[1,0]
	v_pk_mul_f32 v[68:69], v[68:69], v[76:77]
	v_pk_mul_f32 v[72:73], v[72:73], v[80:81]
	v_pk_mul_f32 v[74:75], v[74:75], v[82:83]
	v_pk_mul_f32 v[64:65], v[64:65], v[168:169] op_sel_hi:[1,0]
	v_pk_mul_f32 v[66:67], v[66:67], v[168:169] op_sel_hi:[1,0]
	v_pk_mul_f32 v[70:71], v[70:71], v[78:79]
	v_pk_mul_f32 v[74:75], v[66:67], v[74:75]
	v_pk_mul_f32 v[66:67], v[64:65], v[72:73]
	v_cvt_pk_bf16_f32 v64, v68, v69
	v_mad_i64_i32 v[68:69], s[26:27], v158, s47, v[112:113]
	v_pk_mul_f32 v[60:61], v[60:61], v[164:165] op_sel_hi:[1,0]
	v_cvt_pk_bf16_f32 v65, v70, v71
	v_cvt_pk_bf16_f32 v66, v66, v67
	v_cvt_pk_bf16_f32 v67, v74, v75
	v_pk_mul_f32 v[62:63], v[62:63], v[164:165] op_sel_hi:[1,0]
	v_mul_f32_e32 v70, 0xbfb8aa3b, v60
	v_mul_f32_e32 v71, 0xbfb8aa3b, v61
	v_lshl_add_u64 v[68:69], v[68:69], 0, v[114:115]
	v_pk_mul_f32 v[56:57], v[56:57], v[164:165] op_sel_hi:[1,0]
	v_pk_mul_f32 v[58:59], v[58:59], v[164:165] op_sel_hi:[1,0]
	v_exp_f32_e32 v70, v70
	v_exp_f32_e32 v71, v71
	v_mul_f32_e32 v72, 0xbfb8aa3b, v62
	v_mul_f32_e32 v73, 0xbfb8aa3b, v63
	global_store_dwordx4 v[68:69], v[64:67], off nt
	v_exp_f32_e32 v72, v72
	v_exp_f32_e32 v73, v73
	v_mul_f32_e32 v64, 0xbfb8aa3b, v56
	v_mul_f32_e32 v65, 0xbfb8aa3b, v57
	v_mul_f32_e32 v66, 0xbfb8aa3b, v58
	v_mul_f32_e32 v67, 0xbfb8aa3b, v59
	v_exp_f32_e32 v64, v64
	v_exp_f32_e32 v65, v65
	v_exp_f32_e32 v66, v66
	v_exp_f32_e32 v67, v67
	v_add_f32_e32 v70, 1.0, v70
	v_add_f32_e32 v71, 1.0, v71
	v_rcp_f32_e32 v70, v70
	v_rcp_f32_e32 v71, v71
	v_add_f32_e32 v72, 1.0, v72
	v_add_f32_e32 v73, 1.0, v73
	v_add_f32_e32 v64, 1.0, v64
	v_add_f32_e32 v65, 1.0, v65
	v_add_f32_e32 v66, 1.0, v66
	v_add_f32_e32 v67, 1.0, v67
	v_rcp_f32_e32 v72, v72
	v_rcp_f32_e32 v73, v73
	v_rcp_f32_e32 v64, v64
	v_rcp_f32_e32 v65, v65
	v_rcp_f32_e32 v66, v66
	v_rcp_f32_e32 v67, v67
	v_pk_mul_f32 v[60:61], v[60:61], v[70:71]
	v_pk_mul_f32 v[52:53], v[52:53], v[164:165] op_sel_hi:[1,0]
; __device__ __forceinline__ unsigned cvt_pk_bf16(float lo, float hi) { unsigned r; asm volatile("v_cvt_pk_bf16_f32 %0, %1, %2" : "=v"(r) : "v"(lo), "v"(hi)); return r; }
; __device__ __forceinline__ float silu_f(float v) { return v * __builtin_amdgcn_rcpf(1.0f + __builtin_amdgcn_exp2f(v * -1.4426950408889634f)); }
; __device__ __forceinline__ f32x4 silu4(f32x4 v) { return (f32x4){silu_f(v[0]), silu_f(v[1]), silu_f(v[2]), silu_f(v[3])}; }
; __device__ __forceinline__ float sq4(f32x4 v) { return (v[0] * v[0] + v[1] * v[1]) + (v[2] * v[2] + v[3] * v[3]); }
; __device__ __forceinline__ u32x4 pack8(f32x4 a, f32x4 b) { u32x4 w; w.x = cvt_pk_bf16(a[0], a[1]); w.y = cvt_pk_bf16(a[2], a[3]); w.z = cvt_pk_bf16(b[0], b[1]); w.w = cvt_pk_bf16(b[2], b[3]); return w; }
;     __device__ __forceinline__ void operator()(const f32x4 (&acc)[2][2][4][2], const Unit& u, int wr, int wc, int fr, int fq) const {
;     ...
;         for (int ai = 0; ai < 2; ++ai)
; #pragma unroll
;             for (int m = 0; m < 4; ++m) {
;                 const int row = u.pm * BM + ai * HALF + wr * 64 + m * 16 + fr;
;                 const float rstd = rs[ai][m];
;                 const f32x4 a0 = silu4(acc[ai][0][m][0] * rstd) * (acc[ai][1][m][0] * rstd);
;                 const f32x4 a1 = silu4(acc[ai][0][m][1] * rstd) * (acc[ai][1][m][1] * rstd);
;                 *(u32x4*)(ACT + (size_t)row * 2816 + col0) = pack8(a0, a1);
;             }
	v_pk_mul_f32 v[62:63], v[62:63], v[72:73]
	v_pk_mul_f32 v[54:55], v[54:55], v[164:165] op_sel_hi:[1,0]
	v_pk_mul_f32 v[52:53], v[52:53], v[60:61]
	v_pk_mul_f32 v[56:57], v[56:57], v[64:65]
	v_pk_mul_f32 v[58:59], v[58:59], v[66:67]
	v_pk_mul_f32 v[48:49], v[48:49], v[164:165] op_sel_hi:[1,0]
	v_pk_mul_f32 v[50:51], v[50:51], v[164:165] op_sel_hi:[1,0]
	v_pk_mul_f32 v[54:55], v[54:55], v[62:63]
	v_pk_mul_f32 v[58:59], v[50:51], v[58:59]
	v_pk_mul_f32 v[50:51], v[48:49], v[56:57]
	v_cvt_pk_bf16_f32 v48, v52, v53
	v_mad_i64_i32 v[52:53], s[26:27], v154, s47, v[112:113]
	v_pk_mul_f32 v[44:45], v[44:45], v[160:161] op_sel_hi:[1,0]
	v_cvt_pk_bf16_f32 v49, v54, v55
	v_cvt_pk_bf16_f32 v50, v50, v51
	v_cvt_pk_bf16_f32 v51, v58, v59
	v_pk_mul_f32 v[46:47], v[46:47], v[160:161] op_sel_hi:[1,0]
	v_mul_f32_e32 v54, 0xbfb8aa3b, v44
	v_mul_f32_e32 v55, 0xbfb8aa3b, v45
	v_lshl_add_u64 v[52:53], v[52:53], 0, v[114:115]
	v_pk_mul_f32 v[40:41], v[40:41], v[160:161] op_sel_hi:[1,0]
	v_pk_mul_f32 v[42:43], v[42:43], v[160:161] op_sel_hi:[1,0]
	v_exp_f32_e32 v54, v54
	v_exp_f32_e32 v55, v55
	v_mul_f32_e32 v56, 0xbfb8aa3b, v46
	v_mul_f32_e32 v57, 0xbfb8aa3b, v47
	global_store_dwordx4 v[52:53], v[48:51], off nt
	v_exp_f32_e32 v56, v56
	v_exp_f32_e32 v57, v57
	v_mul_f32_e32 v48, 0xbfb8aa3b, v40
	v_mul_f32_e32 v49, 0xbfb8aa3b, v41
	v_mul_f32_e32 v50, 0xbfb8aa3b, v42
	v_mul_f32_e32 v51, 0xbfb8aa3b, v43
	v_exp_f32_e32 v48, v48
	v_exp_f32_e32 v49, v49
	v_exp_f32_e32 v50, v50
	v_exp_f32_e32 v51, v51
	v_add_f32_e32 v54, 1.0, v54
	v_add_f32_e32 v55, 1.0, v55
	v_rcp_f32_e32 v54, v54
	v_rcp_f32_e32 v55, v55
	v_add_f32_e32 v56, 1.0, v56
	v_add_f32_e32 v57, 1.0, v57
	v_add_f32_e32 v48, 1.0, v48
	v_add_f32_e32 v49, 1.0, v49
	v_add_f32_e32 v50, 1.0, v50
	v_add_f32_e32 v51, 1.0, v51
	v_rcp_f32_e32 v56, v56
	v_rcp_f32_e32 v57, v57
	v_rcp_f32_e32 v48, v48
	v_rcp_f32_e32 v49, v49
	v_rcp_f32_e32 v50, v50
	v_rcp_f32_e32 v51, v51
	v_pk_mul_f32 v[44:45], v[44:45], v[54:55]
	v_pk_mul_f32 v[36:37], v[36:37], v[160:161] op_sel_hi:[1,0]
	v_pk_mul_f32 v[46:47], v[46:47], v[56:57]
	v_pk_mul_f32 v[38:39], v[38:39], v[160:161] op_sel_hi:[1,0]
	v_pk_mul_f32 v[36:37], v[36:37], v[44:45]
	v_pk_mul_f32 v[40:41], v[40:41], v[48:49]
	v_pk_mul_f32 v[42:43], v[42:43], v[50:51]
	v_pk_mul_f32 v[32:33], v[32:33], v[160:161] op_sel_hi:[1,0]
	v_pk_mul_f32 v[34:35], v[34:35], v[160:161] op_sel_hi:[1,0]
	v_pk_mul_f32 v[38:39], v[38:39], v[46:47]
	v_pk_mul_f32 v[42:43], v[34:35], v[42:43]
	v_pk_mul_f32 v[34:35], v[32:33], v[40:41]
	v_cvt_pk_bf16_f32 v32, v36, v37
	v_mad_i64_i32 v[36:37], s[26:27], v150, s47, v[112:113]
	v_pk_mul_f32 v[28:29], v[28:29], v[156:157] op_sel_hi:[1,0]
	v_cvt_pk_bf16_f32 v33, v38, v39
	v_cvt_pk_bf16_f32 v34, v34, v35
	v_cvt_pk_bf16_f32 v35, v42, v43
	v_pk_mul_f32 v[30:31], v[30:31], v[156:157] op_sel_hi:[1,0]
	v_mul_f32_e32 v38, 0xbfb8aa3b, v28
	v_mul_f32_e32 v39, 0xbfb8aa3b, v29
	v_lshl_add_u64 v[36:37], v[36:37], 0, v[114:115]
	v_pk_mul_f32 v[24:25], v[24:25], v[156:157] op_sel_hi:[1,0]
	v_pk_mul_f32 v[26:27], v[26:27], v[156:157] op_sel_hi:[1,0]
	v_exp_f32_e32 v38, v38
	v_exp_f32_e32 v39, v39
	v_mul_f32_e32 v40, 0xbfb8aa3b, v30
	v_mul_f32_e32 v41, 0xbfb8aa3b, v31
	global_store_dwordx4 v[36:37], v[32:35], off nt
	v_exp_f32_e32 v40, v40
	v_exp_f32_e32 v41, v41
	v_mul_f32_e32 v32, 0xbfb8aa3b, v24
	v_mul_f32_e32 v33, 0xbfb8aa3b, v25
	v_mul_f32_e32 v34, 0xbfb8aa3b, v26
	v_mul_f32_e32 v35, 0xbfb8aa3b, v27
	v_exp_f32_e32 v32, v32
	v_exp_f32_e32 v33, v33
	v_exp_f32_e32 v34, v34
	v_exp_f32_e32 v35, v35
	v_add_f32_e32 v38, 1.0, v38
	v_add_f32_e32 v39, 1.0, v39
	v_rcp_f32_e32 v38, v38
	v_rcp_f32_e32 v39, v39
	v_add_f32_e32 v40, 1.0, v40
	v_add_f32_e32 v41, 1.0, v41
	v_add_f32_e32 v32, 1.0, v32
	v_add_f32_e32 v33, 1.0, v33
	v_add_f32_e32 v34, 1.0, v34
	v_add_f32_e32 v35, 1.0, v35
	v_rcp_f32_e32 v40, v40
	v_rcp_f32_e32 v41, v41
	v_rcp_f32_e32 v32, v32
	v_rcp_f32_e32 v33, v33
	v_rcp_f32_e32 v34, v34
	v_rcp_f32_e32 v35, v35
	v_pk_mul_f32 v[28:29], v[28:29], v[38:39]
	v_pk_mul_f32 v[20:21], v[20:21], v[156:157] op_sel_hi:[1,0]
	v_pk_mul_f32 v[30:31], v[30:31], v[40:41]
	v_pk_mul_f32 v[22:23], v[22:23], v[156:157] op_sel_hi:[1,0]
	v_pk_mul_f32 v[20:21], v[20:21], v[28:29]
	v_pk_mul_f32 v[24:25], v[24:25], v[32:33]
	v_pk_mul_f32 v[26:27], v[26:27], v[34:35]
	v_pk_mul_f32 v[16:17], v[16:17], v[156:157] op_sel_hi:[1,0]
	v_pk_mul_f32 v[18:19], v[18:19], v[156:157] op_sel_hi:[1,0]
	v_pk_mul_f32 v[22:23], v[22:23], v[30:31]
	v_pk_mul_f32 v[26:27], v[18:19], v[26:27]
	v_pk_mul_f32 v[18:19], v[16:17], v[24:25]
	v_cvt_pk_bf16_f32 v16, v20, v21
	v_mad_i64_i32 v[20:21], s[26:27], v148, s47, v[112:113]
	v_pk_mul_f32 v[12:13], v[12:13], v[152:153] op_sel_hi:[1,0]
	v_cvt_pk_bf16_f32 v17, v22, v23
	v_cvt_pk_bf16_f32 v18, v18, v19
	v_cvt_pk_bf16_f32 v19, v26, v27
	v_lshl_add_u64 v[20:21], v[20:21], 0, v[114:115]
	v_mul_f32_e32 v22, 0xbfb8aa3b, v12
	v_mul_f32_e32 v23, 0xbfb8aa3b, v13
	v_pk_mul_f32 v[8:9], v[8:9], v[152:153] op_sel_hi:[1,0]
	v_pk_mul_f32 v[10:11], v[10:11], v[152:153] op_sel_hi:[1,0]
	v_exp_f32_e32 v22, v22
	v_exp_f32_e32 v23, v23
	global_store_dwordx4 v[20:21], v[16:19], off nt
	v_pk_mul_f32 v[14:15], v[14:15], v[152:153] op_sel_hi:[1,0]
	v_add_f32_e32 v22, 1.0, v22
	v_mul_f32_e32 v16, 0xbfb8aa3b, v8
	v_mul_f32_e32 v17, 0xbfb8aa3b, v9
	v_mul_f32_e32 v18, 0xbfb8aa3b, v10
	v_mul_f32_e32 v19, 0xbfb8aa3b, v11
	v_exp_f32_e32 v16, v16
	v_exp_f32_e32 v17, v17
	v_exp_f32_e32 v18, v18
	v_exp_f32_e32 v19, v19
	v_mul_f32_e32 v24, 0xbfb8aa3b, v14
	v_mul_f32_e32 v25, 0xbfb8aa3b, v15
	v_exp_f32_e32 v24, v24
	v_exp_f32_e32 v25, v25
	v_add_f32_e32 v23, 1.0, v23
	v_rcp_f32_e32 v22, v22
	v_rcp_f32_e32 v23, v23
	v_add_f32_e32 v16, 1.0, v16
	v_add_f32_e32 v17, 1.0, v17
	v_add_f32_e32 v18, 1.0, v18
	v_add_f32_e32 v19, 1.0, v19
	v_rcp_f32_e32 v16, v16
	v_rcp_f32_e32 v17, v17
	v_rcp_f32_e32 v18, v18
	v_rcp_f32_e32 v19, v19
	v_add_f32_e32 v24, 1.0, v24
	v_add_f32_e32 v25, 1.0, v25
	v_rcp_f32_e32 v24, v24
	v_rcp_f32_e32 v25, v25
	v_pk_mul_f32 v[12:13], v[12:13], v[22:23]
	v_pk_mul_f32 v[4:5], v[4:5], v[152:153] op_sel_hi:[1,0]
	v_pk_mul_f32 v[8:9], v[8:9], v[16:17]
	v_pk_mul_f32 v[4:5], v[4:5], v[12:13]
	v_pk_mul_f32 v[10:11], v[10:11], v[18:19]
	v_pk_mul_f32 v[0:1], v[0:1], v[152:153] op_sel_hi:[1,0]
	v_pk_mul_f32 v[2:3], v[2:3], v[152:153] op_sel_hi:[1,0]
	v_pk_mul_f32 v[14:15], v[14:15], v[24:25]
	v_pk_mul_f32 v[10:11], v[2:3], v[10:11]
	v_pk_mul_f32 v[2:3], v[0:1], v[8:9]
	v_cvt_pk_bf16_f32 v0, v4, v5
	v_mad_i64_i32 v[4:5], s[26:27], v146, s47, v[112:113]
	v_pk_mul_f32 v[6:7], v[6:7], v[152:153] op_sel_hi:[1,0]
	v_lshl_add_u64 v[4:5], v[4:5], 0, v[114:115]
	v_pk_mul_f32 v[6:7], v[6:7], v[14:15]
	s_nop 0
	v_cvt_pk_bf16_f32 v1, v6, v7
	v_cvt_pk_bf16_f32 v2, v2, v3
	v_cvt_pk_bf16_f32 v3, v10, v11
	global_store_dwordx4 v[4:5], v[0:3], off nt
	s_cbranch_vccnz .LBB0_2036
	s_andn2_b64 vcc, exec, s[8:9]
	s_cbranch_vccnz .LBB0_2035
	s_barrier
	s_branch .LBB0_2035
